# attention K/V staging by global_load_lds_dwordx4 (LDS-DMA, source-side permutation keeps the swizzled images), 3-deep LDS ring, no VGPR staging / ds_write
# speedup vs baseline: 1.0970x; 1.0233x over previous
; __device__ __forceinline__ unsigned char* opq(unsigned char* q) { asm volatile("" : "+s"(q)); return q; }
; __device__ __forceinline__ void attn_unit(const bf16_t* __restrict__ Qb, const bf16_t* __restrict__ Kn, const bf16_t* __restrict__ Kr, const bf16_t* __restrict__ Vh,
;                                           bf16_t* __restrict__ Ob, char* lds) {
;   const int tid = opaque_tid(), wid = tid >> 6, lane = tid & 63, r32 = lane & 31, hi = lane >> 5;
;   char* V_lds = lds; char* K_lds = lds + 2 * SHM_V;
;   float* ws = (float*)(lds + 2 * SHM_V + 2 * SHM_K) + wid * 64; float* li_l = ws; float* al_l = ws + 32;
;   float m_reg = 0.f, l_reg = 0; f32x16 o[4] = {}; bf16x8 qr[8];
;   char* qL = lds + 2 * SHM_V + 2 * SHM_K + 2048 + wid * 4096 + lane * 16;
;   const bf16_t* Qw = Qb + (long)(wid * 32 + r32) * 192 + hi * 8;
; #pragma unroll
;   for (int d0 = 0; d0 < 8; ++d0) qr[d0] = *reinterpret_cast<const bf16x8*>(Qw + d0 * 16);
; #pragma unroll
;   for (int d0 = 8; d0 < 12; ++d0) *reinterpret_cast<bf16x8*>(qL + (d0 - 8) * 1024) = *reinterpret_cast<const bf16x8*>(Qw + d0 * 16);
;   const int sr = tid >> 4, sc = (tid & 15) * 8, vst0 = v_st(sr, sc), vst1 = v_st(32 + sr, sc);
;   const int rr = tid >> 3, rc = (tid & 7) * 8;
;   const int kst0 = KSWZ(sr, sc * 2), kst1 = KSWZ(32 + sr, sc * 2), kst2 = KSWZ(rr, 256 + rc * 2);
;   const int vb0 = (int)(uintptr_t)V_lds + v_rd_base(lane);
;   struct { bf16x8 vs0, vs1, ks0, ks1, ks2; } sr_[SDEPTH];
; __global__ void __launch_bounds__(512, 2) mega_fwd(KArgs a) {
;     ...
;         { const bool x8 = (G % 8) == 0; const int xcd = bx & 7, slot = bx >> 3, nslot = G >> 3;
;           for (int pr = 0; pr < (x8 ? 2 : 16); ++pr) { const int p = x8 ? xcd + 8 * pr : pr, b = p >> 3, h = p & 7;
;             for (int qb = x8 ? slot : bx; qb < 64; qb += x8 ? nslot : G) {
;               const bf16_t* Qb = (const bf16_t*)(opq(a.ws) + WS_Q) + ((size_t)(b * 8 + h) * T + (size_t)qb * 256) * 192;
;               const bf16_t* Kn = (const bf16_t*)(opq(a.ws) + WS_KN) + (size_t)(b * 8 + h) * T * 128;
;               const bf16_t* Kr = (const bf16_t*)(opq(a.ws) + WS_KR) + (size_t)b * T * 64;
;               const bf16_t* Vh = (const bf16_t*)(opq(a.ws) + WS_V) + (size_t)(b * 8 + h) * T * 128;
;               bf16_t* Ob = (bf16_t*)(opq(a.ws) + WS_XN) + ((size_t)b * T + (size_t)qb * 256) * DM + 1024 + h * 128;
.LBB0_465:
.LBB0_466:
	s_mul_i32 s41, s16, 0x18000
	s_mul_hi_u32 s42, s16, 0x18000
	s_add_u32 s20, s68, s28
	s_addc_u32 s21, s69, s5
	s_add_u32 s20, s20, s41
	s_addc_u32 s21, s21, s42
	s_add_u32 s20, s20, 0x23300000
	s_addc_u32 s21, s21, 0
	s_add_u32 s24, s68, s14
	s_addc_u32 s25, s69, s15
	s_add_u32 s26, s24, 0x2d300000
	s_addc_u32 s27, s25, 0
	s_add_u32 s24, s24, 0x29300000
	s_addc_u32 s25, s25, 0
	s_add_u32 s30, s68, s8
	s_addc_u32 s31, s69, s9
	s_add_u32 s30, s30, 0x31300000
	s_addc_u32 s31, s31, 0
	s_lshl_b32 s41, s16, 20
	s_add_u32 s36, s68, s10
	s_addc_u32 s37, s69, s11
	s_add_u32 s36, s36, s41
	s_addc_u32 s37, s37, 0
	s_add_u32 s36, s36, s29
	s_addc_u32 s37, s37, 0
	s_add_u32 s36, s36, 0x6300800
	s_addc_u32 s37, s37, 0
	s_mov_b32 s38, 0x4138aa3b
	s_mov_b32 s22, 0x4000
	s_mov_b32 s23, 0
	v_and_b32_e32 v234, 63, v195
	v_lshrrev_b32_e32 v235, 6, v195
	v_and_b32_e32 v243, 15, v234
	v_readfirstlane_b32 s40, v235
	v_lshrrev_b32_e32 v244, 4, v234
	s_mul_i32 s41, s40, 0x3000
	s_add_u32 s20, s20, s41
	s_addc_u32 s21, s21, 0
	s_lshl_b32 s41, s40, 17
	s_add_u32 s36, s36, s41
	s_addc_u32 s37, s37, 0
	s_lshl_b32 s43, s40, 10
	v_mul_u32_u24_e32 v245, 0x180, v243
	v_lshl_add_u32 v245, v244, 4, v245
	v_add_u32_e32 v246, 0x1800, v245
	global_load_dwordx4 v[64:67], v245, s[20:21] offset:0
	global_load_dwordx4 v[68:71], v245, s[20:21] offset:64
	global_load_dwordx4 v[72:75], v245, s[20:21] offset:128
	global_load_dwordx4 v[76:79], v245, s[20:21] offset:192
	global_load_dwordx4 v[80:83], v245, s[20:21] offset:256
	global_load_dwordx4 v[84:87], v245, s[20:21] offset:320
	global_load_dwordx4 v[88:91], v246, s[20:21] offset:0
	global_load_dwordx4 v[92:95], v246, s[20:21] offset:64
	global_load_dwordx4 v[96:99], v246, s[20:21] offset:128
	global_load_dwordx4 v[100:103], v246, s[20:21] offset:192
	global_load_dwordx4 v[104:107], v246, s[20:21] offset:256
	global_load_dwordx4 v[108:111], v246, s[20:21] offset:320
	v_lshlrev_b32_e32 v247, 4, v234
	v_add_u32_e32 v247, s43, v247
	v_mov_b32_e32 v248, v247
	v_mul_u32_u24_e32 v249, 0xaaab, v248
	v_lshrrev_b32_e32 v249, 24, v249
	v_mul_u32_u24_e32 v250, 0x180, v249
	v_sub_u32_e32 v250, v248, v250
	v_lshrrev_b32_e32 v250, 4, v250
	v_and_b32_e32 v251, 7, v249
	v_xor_b32_e32 v196, v250, v251
	v_lshlrev_b32_e32 v196, 4, v196
	v_lshl_add_u32 v196, v249, 8, v196
	v_add_u32_e32 v197, -16, v250
	v_xor_b32_e32 v197, v197, v251
	v_lshlrev_b32_e32 v197, 4, v197
	v_lshl_add_u32 v197, v249, 7, v197
	v_cmp_le_u32_e64 s[34:35], 16, v250
	v_mov_b32_e32 v199, s25
	v_add_co_u32_e32 v198, vcc, s24, v196
	s_nop 1
	v_addc_co_u32_e32 v199, vcc, 0, v199, vcc
	v_mov_b32_e32 v223, s31
	v_add_co_u32_e32 v222, vcc, s30, v197
	s_nop 1
	v_addc_co_u32_e32 v223, vcc, 0, v223, vcc
	v_cndmask_b32_e64 v178, v198, v222, s[34:35]
	v_cndmask_b32_e64 v179, v199, v223, s[34:35]
	v_mov_b32_e32 v198, 0x4000
	v_mov_b32_e32 v222, 0x2000
	v_cndmask_b32_e64 v188, v198, v222, s[34:35]
	v_mov_b32_e32 v189, 0
	v_add_u32_e32 v248, 8192, v247
	v_mul_u32_u24_e32 v249, 0xaaab, v248
	v_lshrrev_b32_e32 v249, 24, v249
	v_mul_u32_u24_e32 v250, 0x180, v249
	v_sub_u32_e32 v250, v248, v250
	v_lshrrev_b32_e32 v250, 4, v250
	v_and_b32_e32 v251, 7, v249
	v_xor_b32_e32 v196, v250, v251
	v_lshlrev_b32_e32 v196, 4, v196
	v_lshl_add_u32 v196, v249, 8, v196
	v_add_u32_e32 v197, -16, v250
	v_xor_b32_e32 v197, v197, v251
	v_lshlrev_b32_e32 v197, 4, v197
	v_lshl_add_u32 v197, v249, 7, v197
	v_cmp_le_u32_e64 s[34:35], 16, v250
	v_mov_b32_e32 v199, s25
	v_add_co_u32_e32 v198, vcc, s24, v196
	s_nop 1
	v_addc_co_u32_e32 v199, vcc, 0, v199, vcc
	v_mov_b32_e32 v223, s31
	v_add_co_u32_e32 v222, vcc, s30, v197
	s_nop 1
	v_addc_co_u32_e32 v223, vcc, 0, v223, vcc
	v_cndmask_b32_e64 v180, v198, v222, s[34:35]
	v_cndmask_b32_e64 v181, v199, v223, s[34:35]
	v_mov_b32_e32 v198, 0x4000
	v_mov_b32_e32 v222, 0x2000
	v_cndmask_b32_e64 v190, v198, v222, s[34:35]
	v_mov_b32_e32 v191, 0
	v_add_u32_e32 v248, 16384, v247
	v_mul_u32_u24_e32 v249, 0xaaab, v248
	v_lshrrev_b32_e32 v249, 24, v249
	v_mul_u32_u24_e32 v250, 0x180, v249
	v_sub_u32_e32 v250, v248, v250
	v_lshrrev_b32_e32 v250, 4, v250
	v_and_b32_e32 v251, 7, v249
	v_xor_b32_e32 v196, v250, v251
	v_lshlrev_b32_e32 v196, 4, v196
	v_lshl_add_u32 v196, v249, 8, v196
	v_add_u32_e32 v197, -16, v250
	v_xor_b32_e32 v197, v197, v251
	v_lshlrev_b32_e32 v197, 4, v197
	v_lshl_add_u32 v197, v249, 7, v197
	v_cmp_le_u32_e64 s[34:35], 16, v250
	v_mov_b32_e32 v199, s25
	v_add_co_u32_e32 v198, vcc, s24, v196
	s_nop 1
	v_addc_co_u32_e32 v199, vcc, 0, v199, vcc
	v_mov_b32_e32 v223, s31
	v_add_co_u32_e32 v222, vcc, s30, v197
	s_nop 1
	v_addc_co_u32_e32 v223, vcc, 0, v223, vcc
	v_cndmask_b32_e64 v182, v198, v222, s[34:35]
	v_cndmask_b32_e64 v183, v199, v223, s[34:35]
	v_mov_b32_e32 v198, 0x4000
	v_mov_b32_e32 v222, 0x2000
	v_cndmask_b32_e64 v192, v198, v222, s[34:35]
	v_mov_b32_e32 v193, 0
	v_mov_b32_e32 v248, v247
	v_lshrrev_b32_e32 v249, 8, v248
	v_and_b32_e32 v250, 7, v249
	v_bfe_u32 v251, v248, 5, 3
	v_xor_b32_e32 v251, v251, v250
	v_lshrrev_b32_e32 v196, 3, v249
	v_lshl_or_b32 v196, v196, 3, v251
	v_lshlrev_b32_e32 v196, 8, v196
	v_lshl_add_u32 v196, v250, 5, v196
	v_and_b32_e32 v251, 16, v248
	v_add_u32_e32 v196, v196, v251
	v_mov_b32_e32 v185, s27
	v_add_co_u32_e32 v184, vcc, s26, v196
	s_nop 1
	v_addc_co_u32_e32 v185, vcc, 0, v185, vcc
	v_add_u32_e32 v248, 8192, v247
	v_lshrrev_b32_e32 v249, 8, v248
	v_and_b32_e32 v250, 7, v249
	v_bfe_u32 v251, v248, 5, 3
	v_xor_b32_e32 v251, v251, v250
	v_lshrrev_b32_e32 v196, 3, v249
	v_lshl_or_b32 v196, v196, 3, v251
	v_lshlrev_b32_e32 v196, 8, v196
	v_lshl_add_u32 v196, v250, 5, v196
	v_and_b32_e32 v251, 16, v248
; __device__ __forceinline__ int v_st(int k, int c) { const int kk = (k & ~0xC) | ((k & 4) << 1) | ((k & 8) >> 1); return ((kk >> 3) * 4 + (c >> 5)) * 512 + ((kk & 7) * 32 + (c & 31)) * 2; }
; __device__ __forceinline__ int v_rd_base(int lane) { return ((lane & 3) << 3) | (((lane >> 2) & 3) << 6) | (((lane >> 4) & 1) << 5) | (((lane >> 5) & 1) << 8); }
; #define SLOAD(i, k0) do { sr_[i].vs0 = *(const bf16x8*)(&Vh[(long)((k0) + sr) * 128 + sc]); sr_[i].vs1 = *(const bf16x8*)(&Vh[(long)((k0) + 32 + sr) * 128 + sc]); \
;     sr_[i].ks0 = *(const bf16x8*)(&Kn[(long)((k0) + sr) * 128 + sc]); sr_[i].ks1 = *(const bf16x8*)(&Kn[(long)((k0) + 32 + sr) * 128 + sc]); \
;     sr_[i].ks2 = *(const bf16x8*)(&Kr[(long)((k0) + rr) * 64 + rc]); } while (0)
; #define SWRITE(b, i) do { *(bf16x8*)(V_lds + (b) * SHM_V + vst0) = sr_[i].vs0; *(bf16x8*)(V_lds + (b) * SHM_V + vst1) = sr_[i].vs1; \
;     *(bf16x8*)(K_lds + (b) * SHM_K + kst0) = sr_[i].ks0; *(bf16x8*)(K_lds + (b) * SHM_K + kst1) = sr_[i].ks1; *(bf16x8*)(K_lds + (b) * SHM_K + kst2) = sr_[i].ks2; } while (0)
; __device__ __forceinline__ void attn_unit(const bf16_t* __restrict__ Qb, const bf16_t* __restrict__ Kn, const bf16_t* __restrict__ Kr, const bf16_t* __restrict__ Vh,
;                                           bf16_t* __restrict__ Ob, char* lds) {
;     ...
;   const int sr = tid >> 4, sc = (tid & 15) * 8, vst0 = v_st(sr, sc), vst1 = v_st(32 + sr, sc);
;   const int rr = tid >> 3, rc = (tid & 7) * 8;
;   const int kst0 = KSWZ(sr, sc * 2), kst1 = KSWZ(32 + sr, sc * 2), kst2 = KSWZ(rr, 256 + rc * 2);
;   const int vb0 = (int)(uintptr_t)V_lds + v_rd_base(lane);
;   struct { bf16x8 vs0, vs1, ks0, ks1, ks2; } sr_[SDEPTH];
;     ...
;   f32x16 pA0, pA1, pB0, pB1; float alA, alB; bf16x8 pa0, pa1, pa2, pa3; const int NT = T / KVBLK;
;   constexpr int SE = 0, SO = SDEPTH - 1;
;   SLOAD(SE, 0); asm volatile("s_waitcnt vmcnt(0)" ::: "memory"); SWRITE(0, SE); __syncthreads();
;   qkt(pA0, pA1, K_lds, qr, qL, r32, hi, 0.f); partialSM<true>(pA0, pA1, m_reg, alA);
;   SLOAD(SO, KVBLK); if constexpr (SDEPTH == 2) { if (2 < NT) SLOAD(SE, 2 * KVBLK); }
	v_add_u32_e32 v196, v196, v251
	v_mov_b32_e32 v187, s27
	v_add_co_u32_e32 v186, vcc, s26, v196
	s_nop 1
	v_addc_co_u32_e32 v187, vcc, 0, v187, vcc
	s_add_i32 m0, s43, 49152
	s_nop 0
	global_load_lds_dwordx4 v[178:179], off
	s_add_i32 m0, s43, 57344
	s_nop 0
	global_load_lds_dwordx4 v[180:181], off
	s_add_i32 m0, s43, 65536
	s_nop 0
	global_load_lds_dwordx4 v[182:183], off
	s_add_i32 m0, s43, 0
	s_nop 0
	global_load_lds_dwordx4 v[184:185], off
	s_add_i32 m0, s43, 8192
	s_nop 0
	global_load_lds_dwordx4 v[186:187], off
	v_lshl_add_u64 v[178:179], v[178:179], 0, v[188:189]
	v_lshl_add_u64 v[180:181], v[180:181], 0, v[190:191]
	v_lshl_add_u64 v[182:183], v[182:183], 0, v[192:193]
	v_lshl_add_u64 v[184:185], v[184:185], 0, s[22:23]
	v_lshl_add_u64 v[186:187], v[186:187], 0, s[22:23]
	s_add_i32 m0, s43, 73728
	s_nop 0
	global_load_lds_dwordx4 v[178:179], off
	s_add_i32 m0, s43, 81920
	s_nop 0
	global_load_lds_dwordx4 v[180:181], off
	s_add_i32 m0, s43, 90112
	s_nop 0
	global_load_lds_dwordx4 v[182:183], off
	s_add_i32 m0, s43, 16384
	s_nop 0
	global_load_lds_dwordx4 v[184:185], off
	s_add_i32 m0, s43, 24576
	s_nop 0
	global_load_lds_dwordx4 v[186:187], off
	v_lshl_add_u64 v[178:179], v[178:179], 0, v[188:189]
	v_lshl_add_u64 v[180:181], v[180:181], 0, v[190:191]
	v_lshl_add_u64 v[182:183], v[182:183], 0, v[192:193]
	v_lshl_add_u64 v[184:185], v[184:185], 0, s[22:23]
	v_lshl_add_u64 v[186:187], v[186:187], 0, s[22:23]
	v_and_b32_e32 v247, 3, v243
	v_xor_b32_e32 v247, v247, v244
	v_mul_u32_u24_e32 v248, 0x180, v243
	v_lshl_add_u32 v248, v247, 4, v248
	v_add_u32_e32 v248, 49152, v248
	v_bfe_u32 v247, v243, 2, 1
	v_lshlrev_b32_e32 v247, 6, v247
	v_add_u32_e32 v202, v248, v247
	v_sub_u32_e32 v203, v248, v247
	v_add_u32_e32 v203, 64, v203
	v_add_u32_e32 v204, 24576, v202
	v_add_u32_e32 v205, 24576, v203
	v_add_u32_e32 v206, 49152, v202
	v_add_u32_e32 v207, 49152, v203
	v_bfe_u32 v247, v234, 4, 1
	v_bfe_u32 v248, v234, 2, 2
	v_lshl_or_b32 v247, v247, 2, v248
	v_lshrrev_b32_e32 v248, 5, v234
	v_lshlrev_b32_e32 v248, 11, v248
	v_and_b32_e32 v249, 3, v234
	v_lshl_or_b32 v248, v249, 3, v248
	v_xor_b32_e32 v249, 0, v247
	v_lshl_add_u32 v208, v249, 5, v248
	v_xor_b32_e32 v249, 1, v247
	v_lshl_add_u32 v209, v249, 5, v248
	v_add_u32_e32 v209, 256, v209
	v_xor_b32_e32 v249, 2, v247
	v_lshl_add_u32 v210, v249, 5, v248
	v_add_u32_e32 v210, 512, v210
	v_xor_b32_e32 v249, 3, v247
	v_lshl_add_u32 v211, v249, 5, v248
	v_add_u32_e32 v211, 768, v211
	v_xor_b32_e32 v249, 4, v247
	v_lshl_add_u32 v212, v249, 5, v248
	v_add_u32_e32 v212, 1024, v212
	v_xor_b32_e32 v249, 5, v247
	v_lshl_add_u32 v213, v249, 5, v248
	v_add_u32_e32 v213, 1280, v213
	v_xor_b32_e32 v249, 6, v247
	v_lshl_add_u32 v214, v249, 5, v248
	v_add_u32_e32 v214, 1536, v214
	v_xor_b32_e32 v249, 7, v247
	v_lshl_add_u32 v215, v249, 5, v248
	v_add_u32_e32 v215, 1792, v215
	s_lshl_b32 s41, s40, 8
	s_add_u32 s41, s41, 122880
	v_lshl_add_u32 v216, v243, 2, s41
	v_lshl_add_u32 v217, v244, 4, s41
	v_xor_b32_e32 v112, 16, v234
	v_lshlrev_b32_e32 v112, 2, v112
	v_mov_b32_e32 v218, 0
	v_mov_b32_e32 v220, 0
	v_mov_b32_e32 v224, 0
	v_mov_b32_e32 v225, 0
	v_mov_b32_e32 v226, 0
	v_mov_b32_e32 v227, 0
	v_mov_b32_e32 v219, 0
	v_mov_b32_e32 v221, 0
	v_mov_b32_e32 v228, 0
	v_mov_b32_e32 v229, 0
	v_mov_b32_e32 v230, 0
	v_mov_b32_e32 v231, 0
	v_mov_b32_e32 v0, 0
	v_mov_b32_e32 v1, 0
	v_mov_b32_e32 v2, 0
	v_mov_b32_e32 v3, 0
	v_mov_b32_e32 v4, 0
	v_mov_b32_e32 v5, 0
	v_mov_b32_e32 v6, 0
	v_mov_b32_e32 v7, 0
	v_mov_b32_e32 v8, 0
	v_mov_b32_e32 v9, 0
	v_mov_b32_e32 v10, 0
	v_mov_b32_e32 v11, 0
	v_mov_b32_e32 v12, 0
	v_mov_b32_e32 v13, 0
	v_mov_b32_e32 v14, 0
	v_mov_b32_e32 v15, 0
	v_mov_b32_e32 v16, 0
	v_mov_b32_e32 v17, 0
	v_mov_b32_e32 v18, 0
	v_mov_b32_e32 v19, 0
	v_mov_b32_e32 v20, 0
	v_mov_b32_e32 v21, 0
	v_mov_b32_e32 v22, 0
	v_mov_b32_e32 v23, 0
	v_mov_b32_e32 v24, 0
	v_mov_b32_e32 v25, 0
	v_mov_b32_e32 v26, 0
	v_mov_b32_e32 v27, 0
	v_mov_b32_e32 v28, 0
	v_mov_b32_e32 v29, 0
	v_mov_b32_e32 v30, 0
	v_mov_b32_e32 v31, 0
	v_mov_b32_e32 v32, 0
	v_mov_b32_e32 v33, 0
	v_mov_b32_e32 v34, 0
	v_mov_b32_e32 v35, 0
	v_mov_b32_e32 v36, 0
	v_mov_b32_e32 v37, 0
	v_mov_b32_e32 v38, 0
	v_mov_b32_e32 v39, 0
	v_mov_b32_e32 v40, 0
	v_mov_b32_e32 v41, 0
	v_mov_b32_e32 v42, 0
	v_mov_b32_e32 v43, 0
	v_mov_b32_e32 v44, 0
	v_mov_b32_e32 v45, 0
	v_mov_b32_e32 v46, 0
	v_mov_b32_e32 v47, 0
	v_mov_b32_e32 v48, 0
	v_mov_b32_e32 v49, 0
	v_mov_b32_e32 v50, 0
	v_mov_b32_e32 v51, 0
	v_mov_b32_e32 v52, 0
	v_mov_b32_e32 v53, 0
	v_mov_b32_e32 v54, 0
	v_mov_b32_e32 v55, 0
	v_mov_b32_e32 v56, 0
	v_mov_b32_e32 v57, 0
	v_mov_b32_e32 v58, 0
	v_mov_b32_e32 v59, 0
	v_mov_b32_e32 v60, 0
	v_mov_b32_e32 v61, 0
	v_mov_b32_e32 v62, 0
	v_mov_b32_e32 v63, 0
	s_waitcnt vmcnt(5)
	s_barrier
; #define SLOAD(i, k0) do { sr_[i].vs0 = *(const bf16x8*)(&Vh[(long)((k0) + sr) * 128 + sc]); sr_[i].vs1 = *(const bf16x8*)(&Vh[(long)((k0) + 32 + sr) * 128 + sc]); \
;     sr_[i].ks0 = *(const bf16x8*)(&Kn[(long)((k0) + sr) * 128 + sc]); sr_[i].ks1 = *(const bf16x8*)(&Kn[(long)((k0) + 32 + sr) * 128 + sc]); \
;     sr_[i].ks2 = *(const bf16x8*)(&Kr[(long)((k0) + rr) * 64 + rc]); } while (0)
; __device__ __forceinline__ void qkt(f32x16& p0, f32x16& p1, const char* Ks, const bf16x8* qr, const char* qL, int r32, int hi, float negm) {
; #pragma unroll
;   for (int r = 0; r < 16; ++r) { p0[r] = negm; p1[r] = negm; }
; #pragma unroll
;   for (int d0 = 0; d0 < 12; ++d0) { int cb = (d0 * 16 + hi * 8) * 2;
;     bf16x8 b0 = *reinterpret_cast<const bf16x8*>(Ks + KSWZ(r32, cb));
;     bf16x8 b1 = *reinterpret_cast<const bf16x8*>(Ks + KSWZ(32 + r32, cb));
;     const bf16x8 q = d0 < 8 ? qr[d0 < 8 ? d0 : 0] : *reinterpret_cast<const bf16x8*>(qL + (d0 - 8) * 1024);
;     p0 = __builtin_amdgcn_mfma_f32_32x32x16_bf16(b0, q, p0, 0, 0, 0);
;     p1 = __builtin_amdgcn_mfma_f32_32x32x16_bf16(b1, q, p1, 0, 0, 0); }
; }
; __device__ __forceinline__ void attn_unit(const bf16_t* __restrict__ Qb, const bf16_t* __restrict__ Kn, const bf16_t* __restrict__ Kr, const bf16_t* __restrict__ Vh,
;                                           bf16_t* __restrict__ Ob, char* lds) {
;     ...
;   qkt(pA0, pA1, K_lds, qr, qL, r32, hi, 0.f); partialSM<true>(pA0, pA1, m_reg, alA);
;   SLOAD(SO, KVBLK); if constexpr (SDEPTH == 2) { if (2 < NT) SLOAD(SE, 2 * KVBLK); }
	s_add_i32 m0, s43, 98304
	s_nop 0
	global_load_lds_dwordx4 v[178:179], off
	s_add_i32 m0, s43, 106496
	s_nop 0
	global_load_lds_dwordx4 v[180:181], off
	s_add_i32 m0, s43, 114688
	s_nop 0
	global_load_lds_dwordx4 v[182:183], off
	s_add_i32 m0, s43, 32768
	s_nop 0
	global_load_lds_dwordx4 v[184:185], off
	s_add_i32 m0, s43, 40960
	s_nop 0
	global_load_lds_dwordx4 v[186:187], off
	v_lshl_add_u64 v[178:179], v[178:179], 0, v[188:189]
	v_lshl_add_u64 v[180:181], v[180:181], 0, v[190:191]
	v_lshl_add_u64 v[182:183], v[182:183], 0, v[192:193]
	v_lshl_add_u64 v[184:185], v[184:185], 0, s[22:23]
	v_lshl_add_u64 v[186:187], v[186:187], 0, s[22:23]
	ds_read_b128 v[162:165], v202 offset:0
	ds_read_b128 v[166:169], v202 offset:6144
	ds_read_b128 v[170:173], v202 offset:12288
	s_waitcnt lgkmcnt(2)
	v_mfma_f32_16x16x32_bf16 v[114:117], v[162:165], v[64:67], v[224:227]
	v_mfma_f32_16x16x32_bf16 v[118:121], v[162:165], v[88:91], v[228:231]
	ds_read_b128 v[174:177], v202 offset:18432
	s_waitcnt lgkmcnt(2)
	v_mfma_f32_16x16x32_bf16 v[126:129], v[166:169], v[88:91], v[228:231]
	v_mfma_f32_16x16x32_bf16 v[122:125], v[166:169], v[64:67], v[224:227]
	ds_read_b128 v[162:165], v203 offset:0
	s_waitcnt lgkmcnt(2)
	v_mfma_f32_16x16x32_bf16 v[130:133], v[170:173], v[64:67], v[224:227]
	v_mfma_f32_16x16x32_bf16 v[134:137], v[170:173], v[88:91], v[228:231]
	ds_read_b128 v[166:169], v203 offset:6144
	s_waitcnt lgkmcnt(2)
	v_mfma_f32_16x16x32_bf16 v[142:145], v[174:177], v[88:91], v[228:231]
	v_mfma_f32_16x16x32_bf16 v[138:141], v[174:177], v[64:67], v[224:227]
	ds_read_b128 v[170:173], v203 offset:12288
	s_waitcnt lgkmcnt(2)
	v_mfma_f32_16x16x32_bf16 v[114:117], v[162:165], v[68:71], v[114:117]
	v_mfma_f32_16x16x32_bf16 v[118:121], v[162:165], v[92:95], v[118:121]
	ds_read_b128 v[174:177], v203 offset:18432
	s_waitcnt lgkmcnt(2)
	v_mfma_f32_16x16x32_bf16 v[126:129], v[166:169], v[92:95], v[126:129]
	v_mfma_f32_16x16x32_bf16 v[122:125], v[166:169], v[68:71], v[122:125]
	ds_read_b128 v[162:165], v202 offset:128
	s_waitcnt lgkmcnt(2)
	v_mfma_f32_16x16x32_bf16 v[130:133], v[170:173], v[68:71], v[130:133]
	v_mfma_f32_16x16x32_bf16 v[134:137], v[170:173], v[92:95], v[134:137]
	ds_read_b128 v[166:169], v202 offset:6272
	s_waitcnt lgkmcnt(2)
	v_mfma_f32_16x16x32_bf16 v[142:145], v[174:177], v[92:95], v[142:145]
	v_mfma_f32_16x16x32_bf16 v[138:141], v[174:177], v[68:71], v[138:141]
	ds_read_b128 v[170:173], v202 offset:12416
	s_waitcnt lgkmcnt(2)
	v_mfma_f32_16x16x32_bf16 v[114:117], v[162:165], v[72:75], v[114:117]
	v_mfma_f32_16x16x32_bf16 v[118:121], v[162:165], v[96:99], v[118:121]
	ds_read_b128 v[174:177], v202 offset:18560
	s_waitcnt lgkmcnt(2)
	v_mfma_f32_16x16x32_bf16 v[126:129], v[166:169], v[96:99], v[126:129]
	v_mfma_f32_16x16x32_bf16 v[122:125], v[166:169], v[72:75], v[122:125]
	ds_read_b128 v[162:165], v203 offset:128
	s_waitcnt lgkmcnt(2)
	v_mfma_f32_16x16x32_bf16 v[130:133], v[170:173], v[72:75], v[130:133]
	v_mfma_f32_16x16x32_bf16 v[134:137], v[170:173], v[96:99], v[134:137]
	ds_read_b128 v[166:169], v203 offset:6272
	s_waitcnt lgkmcnt(2)
	v_mfma_f32_16x16x32_bf16 v[142:145], v[174:177], v[96:99], v[142:145]
	v_mfma_f32_16x16x32_bf16 v[138:141], v[174:177], v[72:75], v[138:141]
	ds_read_b128 v[170:173], v203 offset:12416
	s_waitcnt lgkmcnt(2)
	v_mfma_f32_16x16x32_bf16 v[114:117], v[162:165], v[76:79], v[114:117]
	v_mfma_f32_16x16x32_bf16 v[118:121], v[162:165], v[100:103], v[118:121]
	ds_read_b128 v[174:177], v203 offset:18560
	s_waitcnt lgkmcnt(2)
	v_mfma_f32_16x16x32_bf16 v[126:129], v[166:169], v[100:103], v[126:129]
	v_mfma_f32_16x16x32_bf16 v[122:125], v[166:169], v[76:79], v[122:125]
	ds_read_b128 v[162:165], v202 offset:256
	s_waitcnt lgkmcnt(2)
	v_mfma_f32_16x16x32_bf16 v[130:133], v[170:173], v[76:79], v[130:133]
	v_mfma_f32_16x16x32_bf16 v[134:137], v[170:173], v[100:103], v[134:137]
	ds_read_b128 v[166:169], v202 offset:6400
	s_waitcnt lgkmcnt(2)
	v_mfma_f32_16x16x32_bf16 v[142:145], v[174:177], v[100:103], v[142:145]
	v_mfma_f32_16x16x32_bf16 v[138:141], v[174:177], v[76:79], v[138:141]
	ds_read_b128 v[170:173], v202 offset:12544
	s_waitcnt lgkmcnt(2)
	v_mfma_f32_16x16x32_bf16 v[114:117], v[162:165], v[80:83], v[114:117]
	v_mfma_f32_16x16x32_bf16 v[118:121], v[162:165], v[104:107], v[118:121]
	ds_read_b128 v[174:177], v202 offset:18688
	s_waitcnt lgkmcnt(2)
	v_mfma_f32_16x16x32_bf16 v[126:129], v[166:169], v[104:107], v[126:129]
	v_mfma_f32_16x16x32_bf16 v[122:125], v[166:169], v[80:83], v[122:125]
	ds_read_b128 v[162:165], v203 offset:256
	s_waitcnt lgkmcnt(2)
	v_mfma_f32_16x16x32_bf16 v[130:133], v[170:173], v[80:83], v[130:133]
	v_mfma_f32_16x16x32_bf16 v[134:137], v[170:173], v[104:107], v[134:137]
	ds_read_b128 v[166:169], v203 offset:6400
	s_waitcnt lgkmcnt(2)
	v_mfma_f32_16x16x32_bf16 v[142:145], v[174:177], v[104:107], v[142:145]
	v_mfma_f32_16x16x32_bf16 v[138:141], v[174:177], v[80:83], v[138:141]
	ds_read_b128 v[170:173], v203 offset:12544
	s_waitcnt lgkmcnt(2)
	v_mfma_f32_16x16x32_bf16 v[114:117], v[162:165], v[84:87], v[114:117]
	v_mfma_f32_16x16x32_bf16 v[118:121], v[162:165], v[108:111], v[118:121]
	ds_read_b128 v[174:177], v203 offset:18688
	s_waitcnt lgkmcnt(2)
	v_mfma_f32_16x16x32_bf16 v[126:129], v[166:169], v[108:111], v[126:129]
	v_mfma_f32_16x16x32_bf16 v[122:125], v[166:169], v[84:87], v[122:125]
	s_waitcnt lgkmcnt(1)
	v_mfma_f32_16x16x32_bf16 v[130:133], v[170:173], v[84:87], v[130:133]
	v_mfma_f32_16x16x32_bf16 v[134:137], v[170:173], v[108:111], v[134:137]
	s_waitcnt lgkmcnt(0)
	v_mfma_f32_16x16x32_bf16 v[142:145], v[174:177], v[108:111], v[142:145]
	v_mfma_f32_16x16x32_bf16 v[138:141], v[174:177], v[84:87], v[138:141]
	ds_read_b64_tr_b16 v[162:163], v208 offset:0
	ds_read_b64_tr_b16 v[164:165], v208 offset:4096
	ds_read_b64_tr_b16 v[166:167], v209 offset:0
	ds_read_b64_tr_b16 v[168:169], v209 offset:4096
	ds_read_b64_tr_b16 v[170:171], v210 offset:0
	ds_read_b64_tr_b16 v[172:173], v210 offset:4096
	s_nop 7
	v_max3_f32 v232, v114, v115, v116
	v_max_f32_e32 v232, v232, v117
	v_max3_f32 v233, v118, v119, v120
	v_max_f32_e32 v233, v233, v121
	v_max3_f32 v232, v232, v122, v123
	v_max3_f32 v232, v232, v124, v125
	v_max3_f32 v233, v233, v126, v127
	v_max3_f32 v233, v233, v128, v129
	v_max3_f32 v232, v232, v130, v131
	v_max3_f32 v232, v232, v132, v133
	v_max3_f32 v233, v233, v134, v135
	v_max3_f32 v233, v233, v136, v137
	v_max3_f32 v232, v232, v138, v139
	v_max3_f32 v232, v232, v140, v141
	v_max3_f32 v233, v233, v142, v143
	v_max3_f32 v233, v233, v144, v145
	s_branch .Lat_rare_0
; __device__ __forceinline__ void finishSM(f32x16& p0, f32x16& p1, float alpha, float& l_reg, bf16x8& pa0, bf16x8& pa1, bf16x8& pa2, bf16x8& pa3) {
; #pragma unroll
;   for (int r = 0; r < 16; ++r) p1[r] = __builtin_amdgcn_exp2f(p1[r]);
;   float ps = 0;
; #pragma unroll
;   for (int r = 0; r < 16; ++r) ps += p0[r];
; #pragma unroll
;   for (int r = 0; r < 16; ++r) ps += p1[r];
;   { auto rr = __builtin_amdgcn_permlane32_swap(__float_as_uint(ps), __float_as_uint(ps), false, false);
;     ps = __uint_as_float(rr[0]) + __uint_as_float(rr[1]); }
;   l_reg = l_reg * alpha + ps;
;     ...
;   PK4(p0, 0, pa0); PK4(p0, 8, pa1); PK4(p1, 0, pa2); PK4(p1, 8, pa3);
;     ...
; }
; __device__ __forceinline__ void qkt(f32x16& p0, f32x16& p1, const char* Ks, const bf16x8* qr, const char* qL, int r32, int hi, float negm) {
; #pragma unroll
;   for (int r = 0; r < 16; ++r) { p0[r] = negm; p1[r] = negm; }
; #pragma unroll
;   for (int d0 = 0; d0 < 12; ++d0) { int cb = (d0 * 16 + hi * 8) * 2;
;     bf16x8 b0 = *reinterpret_cast<const bf16x8*>(Ks + KSWZ(r32, cb));
;     bf16x8 b1 = *reinterpret_cast<const bf16x8*>(Ks + KSWZ(32 + r32, cb));
;     const bf16x8 q = d0 < 8 ? qr[d0 < 8 ? d0 : 0] : *reinterpret_cast<const bf16x8*>(qL + (d0 - 8) * 1024);
;     p0 = __builtin_amdgcn_mfma_f32_32x32x16_bf16(b0, q, p0, 0, 0, 0);
;     p1 = __builtin_amdgcn_mfma_f32_32x32x16_bf16(b1, q, p1, 0, 0, 0); }
; }
; __device__ __forceinline__ int v_st(int k, int c) { const int kk = (k & ~0xC) | ((k & 4) << 1) | ((k & 8) >> 1); return ((kk >> 3) * 4 + (c >> 5)) * 512 + ((kk & 7) * 32 + (c & 31)) * 2; }
; __device__ __forceinline__ int v_rd_base(int lane) { return ((lane & 3) << 3) | (((lane >> 2) & 3) << 6) | (((lane >> 4) & 1) << 5) | (((lane >> 5) & 1) << 8); }
; template <int OFF> __device__ __forceinline__ s16x4 tr_read(int vb) {
;   s16x4 r; asm volatile("ds_read_b64_tr_b16 %0, %1 offset:%2" : "=&v"(r) : "v"(vb), "i"(OFF) : "memory"); return r;
; }
; template <int D0> __device__ __forceinline__ void pv_one(f32x16& od, int vb, bf16x8 pa0, bf16x8 pa1, bf16x8 pa2, bf16x8 pa3) {
;   const s16x4 l0 = tr_read<v_rd_off(D0, 0, 0)>(vb), h0 = tr_read<v_rd_off(D0, 0, 1)>(vb), l1 = tr_read<v_rd_off(D0, 1, 0)>(vb), h1 = tr_read<v_rd_off(D0, 1, 1)>(vb);
;   const s16x4 l2 = tr_read<v_rd_off(D0, 2, 0)>(vb), h2 = tr_read<v_rd_off(D0, 2, 1)>(vb), l3 = tr_read<v_rd_off(D0, 3, 0)>(vb), h3 = tr_read<v_rd_off(D0, 3, 1)>(vb);
.Lat_cont_0:
	v_exp_f32_e32 v114, v114
	v_exp_f32_e32 v115, v115
	v_exp_f32_e32 v116, v116
	v_exp_f32_e32 v117, v117
	v_add_f32_e32 v220, v220, v114
	v_add_f32_e32 v220, v220, v115
	v_add_f32_e32 v220, v220, v116
	v_add_f32_e32 v220, v220, v117
	v_exp_f32_e32 v122, v122
	v_exp_f32_e32 v123, v123
	v_exp_f32_e32 v124, v124
	v_exp_f32_e32 v125, v125
	v_add_f32_e32 v220, v220, v122
	v_add_f32_e32 v220, v220, v123
	v_add_f32_e32 v220, v220, v124
	v_add_f32_e32 v220, v220, v125
	v_cvt_pk_bf16_f32 v146, v114, v115
	v_cvt_pk_bf16_f32 v147, v116, v117
	v_cvt_pk_bf16_f32 v148, v122, v123
	v_cvt_pk_bf16_f32 v149, v124, v125
	v_exp_f32_e32 v118, v118
	v_exp_f32_e32 v119, v119
	v_exp_f32_e32 v120, v120
	v_exp_f32_e32 v121, v121
	v_add_f32_e32 v221, v221, v118
	v_add_f32_e32 v221, v221, v119
	v_add_f32_e32 v221, v221, v120
	v_add_f32_e32 v221, v221, v121
	v_exp_f32_e32 v126, v126
	v_exp_f32_e32 v127, v127
	v_exp_f32_e32 v128, v128
	v_exp_f32_e32 v129, v129
	v_add_f32_e32 v221, v221, v126
	v_add_f32_e32 v221, v221, v127
	v_add_f32_e32 v221, v221, v128
	v_add_f32_e32 v221, v221, v129
	v_cvt_pk_bf16_f32 v154, v118, v119
	v_cvt_pk_bf16_f32 v155, v120, v121
	v_cvt_pk_bf16_f32 v156, v126, v127
	v_cvt_pk_bf16_f32 v157, v128, v129
	s_nop 1
	s_waitcnt lgkmcnt(4)
	v_mfma_f32_16x16x32_bf16 v[0:3], v[146:149], v[162:165], v[0:3]
	v_mfma_f32_16x16x32_bf16 v[32:35], v[154:157], v[162:165], v[32:35]
	ds_read_b64_tr_b16 v[174:175], v211 offset:0
	ds_read_b64_tr_b16 v[176:177], v211 offset:4096
	v_exp_f32_e32 v130, v130
	v_exp_f32_e32 v131, v131
	v_exp_f32_e32 v132, v132
	v_exp_f32_e32 v133, v133
	v_add_f32_e32 v220, v220, v130
	s_waitcnt lgkmcnt(4)
	v_mfma_f32_16x16x32_bf16 v[36:39], v[154:157], v[166:169], v[36:39]
	v_mfma_f32_16x16x32_bf16 v[4:7], v[146:149], v[166:169], v[4:7]
	ds_read_b64_tr_b16 v[162:163], v212 offset:0
	ds_read_b64_tr_b16 v[164:165], v212 offset:4096
	v_add_f32_e32 v220, v220, v131
	v_add_f32_e32 v220, v220, v132
	v_add_f32_e32 v220, v220, v133
	v_exp_f32_e32 v138, v138
	v_exp_f32_e32 v139, v139
	s_waitcnt lgkmcnt(4)
	v_mfma_f32_16x16x32_bf16 v[8:11], v[146:149], v[170:173], v[8:11]
	v_mfma_f32_16x16x32_bf16 v[40:43], v[154:157], v[170:173], v[40:43]
	ds_read_b64_tr_b16 v[166:167], v213 offset:0
	ds_read_b64_tr_b16 v[168:169], v213 offset:4096
	v_exp_f32_e32 v140, v140
	v_exp_f32_e32 v141, v141
	v_add_f32_e32 v220, v220, v138
	v_add_f32_e32 v220, v220, v139
	v_add_f32_e32 v220, v220, v140
	s_waitcnt lgkmcnt(4)
	v_mfma_f32_16x16x32_bf16 v[44:47], v[154:157], v[174:177], v[44:47]
	v_mfma_f32_16x16x32_bf16 v[12:15], v[146:149], v[174:177], v[12:15]
	ds_read_b64_tr_b16 v[170:171], v214 offset:0
	ds_read_b64_tr_b16 v[172:173], v214 offset:4096
	v_add_f32_e32 v220, v220, v141
	v_cvt_pk_bf16_f32 v150, v130, v131
	v_cvt_pk_bf16_f32 v151, v132, v133
	v_cvt_pk_bf16_f32 v152, v138, v139
	v_cvt_pk_bf16_f32 v153, v140, v141
	s_waitcnt lgkmcnt(4)
	v_mfma_f32_16x16x32_bf16 v[16:19], v[146:149], v[162:165], v[16:19]
	v_mfma_f32_16x16x32_bf16 v[48:51], v[154:157], v[162:165], v[48:51]
	ds_read_b64_tr_b16 v[174:175], v215 offset:0
	ds_read_b64_tr_b16 v[176:177], v215 offset:4096
	v_exp_f32_e32 v134, v134
	v_exp_f32_e32 v135, v135
	v_exp_f32_e32 v136, v136
	v_exp_f32_e32 v137, v137
	v_add_f32_e32 v221, v221, v134
	s_waitcnt lgkmcnt(4)
	v_mfma_f32_16x16x32_bf16 v[52:55], v[154:157], v[166:169], v[52:55]
	v_mfma_f32_16x16x32_bf16 v[20:23], v[146:149], v[166:169], v[20:23]
	ds_read_b64_tr_b16 v[162:163], v208 offset:8192
	ds_read_b64_tr_b16 v[164:165], v208 offset:12288
	v_add_f32_e32 v221, v221, v135
	v_add_f32_e32 v221, v221, v136
	v_add_f32_e32 v221, v221, v137
	v_exp_f32_e32 v142, v142
	v_exp_f32_e32 v143, v143
	s_waitcnt lgkmcnt(4)
	v_mfma_f32_16x16x32_bf16 v[24:27], v[146:149], v[170:173], v[24:27]
	v_mfma_f32_16x16x32_bf16 v[56:59], v[154:157], v[170:173], v[56:59]
	ds_read_b64_tr_b16 v[166:167], v209 offset:8192
	ds_read_b64_tr_b16 v[168:169], v209 offset:12288
	v_exp_f32_e32 v144, v144
	v_exp_f32_e32 v145, v145
	v_add_f32_e32 v221, v221, v142
	v_add_f32_e32 v221, v221, v143
	v_add_f32_e32 v221, v221, v144
	s_waitcnt lgkmcnt(4)
	v_mfma_f32_16x16x32_bf16 v[60:63], v[154:157], v[174:177], v[60:63]
	v_mfma_f32_16x16x32_bf16 v[28:31], v[146:149], v[174:177], v[28:31]
	ds_read_b64_tr_b16 v[170:171], v210 offset:8192
	ds_read_b64_tr_b16 v[172:173], v210 offset:12288
	v_add_f32_e32 v221, v221, v145
	v_cvt_pk_bf16_f32 v158, v134, v135
	v_cvt_pk_bf16_f32 v159, v136, v137
	v_cvt_pk_bf16_f32 v160, v142, v143
	v_cvt_pk_bf16_f32 v161, v144, v145
	s_waitcnt lgkmcnt(4)
	s_nop 1
	v_mfma_f32_16x16x32_bf16 v[0:3], v[150:153], v[162:165], v[0:3]
	v_mfma_f32_16x16x32_bf16 v[32:35], v[158:161], v[162:165], v[32:35]
	ds_read_b64_tr_b16 v[174:175], v211 offset:8192
	ds_read_b64_tr_b16 v[176:177], v211 offset:12288
	s_waitcnt lgkmcnt(4)
	v_mfma_f32_16x16x32_bf16 v[36:39], v[158:161], v[166:169], v[36:39]
	v_mfma_f32_16x16x32_bf16 v[4:7], v[150:153], v[166:169], v[4:7]
	ds_read_b64_tr_b16 v[162:163], v212 offset:8192
	ds_read_b64_tr_b16 v[164:165], v212 offset:12288
	s_waitcnt lgkmcnt(4)
	v_mfma_f32_16x16x32_bf16 v[8:11], v[150:153], v[170:173], v[8:11]
	v_mfma_f32_16x16x32_bf16 v[40:43], v[158:161], v[170:173], v[40:43]
	ds_read_b64_tr_b16 v[166:167], v213 offset:8192
	ds_read_b64_tr_b16 v[168:169], v213 offset:12288
	s_waitcnt lgkmcnt(4)
	v_mfma_f32_16x16x32_bf16 v[44:47], v[158:161], v[174:177], v[44:47]
	v_mfma_f32_16x16x32_bf16 v[12:15], v[150:153], v[174:177], v[12:15]
	ds_read_b64_tr_b16 v[170:171], v214 offset:8192
	ds_read_b64_tr_b16 v[172:173], v214 offset:12288
	s_waitcnt lgkmcnt(4)
	v_mfma_f32_16x16x32_bf16 v[16:19], v[150:153], v[162:165], v[16:19]
	v_mfma_f32_16x16x32_bf16 v[48:51], v[158:161], v[162:165], v[48:51]
	ds_read_b64_tr_b16 v[174:175], v215 offset:8192
	ds_read_b64_tr_b16 v[176:177], v215 offset:12288
	s_waitcnt lgkmcnt(4)
	v_mfma_f32_16x16x32_bf16 v[52:55], v[158:161], v[166:169], v[52:55]
	v_mfma_f32_16x16x32_bf16 v[20:23], v[150:153], v[166:169], v[20:23]
	s_waitcnt lgkmcnt(2)
	v_mfma_f32_16x16x32_bf16 v[24:27], v[150:153], v[170:173], v[24:27]
	v_mfma_f32_16x16x32_bf16 v[56:59], v[158:161], v[170:173], v[56:59]
	s_waitcnt lgkmcnt(0)
	v_mfma_f32_16x16x32_bf16 v[60:63], v[158:161], v[174:177], v[60:63]
	v_mfma_f32_16x16x32_bf16 v[28:31], v[150:153], v[174:177], v[28:31]
	s_waitcnt vmcnt(5)
	s_barrier
	s_movk_i32 s39, 85
; #define SBAR() __builtin_amdgcn_sched_barrier(0)
; #define SLOAD(i, k0) do { sr_[i].vs0 = *(const bf16x8*)(&Vh[(long)((k0) + sr) * 128 + sc]); sr_[i].vs1 = *(const bf16x8*)(&Vh[(long)((k0) + 32 + sr) * 128 + sc]); \
;     sr_[i].ks0 = *(const bf16x8*)(&Kn[(long)((k0) + sr) * 128 + sc]); sr_[i].ks1 = *(const bf16x8*)(&Kn[(long)((k0) + 32 + sr) * 128 + sc]); \
;     sr_[i].ks2 = *(const bf16x8*)(&Kr[(long)((k0) + rr) * 64 + rc]); } while (0)
; __device__ __forceinline__ void qkt(f32x16& p0, f32x16& p1, const char* Ks, const bf16x8* qr, const char* qL, int r32, int hi, float negm) {
; #pragma unroll
;   for (int r = 0; r < 16; ++r) { p0[r] = negm; p1[r] = negm; }
; #pragma unroll
;   for (int d0 = 0; d0 < 12; ++d0) { int cb = (d0 * 16 + hi * 8) * 2;
;     bf16x8 b0 = *reinterpret_cast<const bf16x8*>(Ks + KSWZ(r32, cb));
;     bf16x8 b1 = *reinterpret_cast<const bf16x8*>(Ks + KSWZ(32 + r32, cb));
;     const bf16x8 q = d0 < 8 ? qr[d0 < 8 ? d0 : 0] : *reinterpret_cast<const bf16x8*>(qL + (d0 - 8) * 1024);
;     p0 = __builtin_amdgcn_mfma_f32_32x32x16_bf16(b0, q, p0, 0, 0, 0);
;     p1 = __builtin_amdgcn_mfma_f32_32x32x16_bf16(b1, q, p1, 0, 0, 0); }
; }
; __device__ __forceinline__ void attn_unit(const bf16_t* __restrict__ Qb, const bf16_t* __restrict__ Kn, const bf16_t* __restrict__ Kr, const bf16_t* __restrict__ Vh,
;                                           bf16_t* __restrict__ Ob, char* lds) {
;     ...
;   for (int j = 1; j + 1 < NT; j += 2) {
;     SBAR(); qkt(pB0, pB1, K_lds + SHM_K, qr, qL, r32, hi, -m_reg);
;     finishSM(pA0, pA1, alA, l_reg, pa0, pa1, pa2, pa3); SBAR();
;     SLOAD(SO, (j + SDEPTH) * KVBLK); SBAR();
;     pv_d0(o, vb0, pa0, pa1, pa2, pa3); partialSM<false>(pB0, pB1, m_reg, alB);
.Lat_loop:
	s_add_i32 m0, s43, 49152
	s_nop 0
	global_load_lds_dwordx4 v[178:179], off
	s_add_i32 m0, s43, 57344
	s_nop 0
	global_load_lds_dwordx4 v[180:181], off
	s_add_i32 m0, s43, 65536
	s_nop 0
	global_load_lds_dwordx4 v[182:183], off
	s_add_i32 m0, s43, 0
	s_nop 0
	global_load_lds_dwordx4 v[184:185], off
	s_add_i32 m0, s43, 8192
	s_nop 0
	global_load_lds_dwordx4 v[186:187], off
	v_lshl_add_u64 v[178:179], v[178:179], 0, v[188:189]
	v_lshl_add_u64 v[180:181], v[180:181], 0, v[190:191]
	v_lshl_add_u64 v[182:183], v[182:183], 0, v[192:193]
	v_lshl_add_u64 v[184:185], v[184:185], 0, s[22:23]
	v_lshl_add_u64 v[186:187], v[186:187], 0, s[22:23]
	ds_read_b128 v[162:165], v204 offset:0
	ds_read_b128 v[166:169], v204 offset:6144
	ds_read_b128 v[170:173], v204 offset:12288
	s_waitcnt lgkmcnt(2)
	v_mfma_f32_16x16x32_bf16 v[114:117], v[162:165], v[64:67], v[224:227]
	v_mfma_f32_16x16x32_bf16 v[118:121], v[162:165], v[88:91], v[228:231]
	ds_read_b128 v[174:177], v204 offset:18432
	s_waitcnt lgkmcnt(2)
	v_mfma_f32_16x16x32_bf16 v[126:129], v[166:169], v[88:91], v[228:231]
	v_mfma_f32_16x16x32_bf16 v[122:125], v[166:169], v[64:67], v[224:227]
	ds_read_b128 v[162:165], v205 offset:0
	s_waitcnt lgkmcnt(2)
	v_mfma_f32_16x16x32_bf16 v[130:133], v[170:173], v[64:67], v[224:227]
	v_mfma_f32_16x16x32_bf16 v[134:137], v[170:173], v[88:91], v[228:231]
	ds_read_b128 v[166:169], v205 offset:6144
	s_waitcnt lgkmcnt(2)
	v_mfma_f32_16x16x32_bf16 v[142:145], v[174:177], v[88:91], v[228:231]
	v_mfma_f32_16x16x32_bf16 v[138:141], v[174:177], v[64:67], v[224:227]
	ds_read_b128 v[170:173], v205 offset:12288
	s_waitcnt lgkmcnt(2)
	v_mfma_f32_16x16x32_bf16 v[114:117], v[162:165], v[68:71], v[114:117]
	v_mfma_f32_16x16x32_bf16 v[118:121], v[162:165], v[92:95], v[118:121]
	ds_read_b128 v[174:177], v205 offset:18432
	s_waitcnt lgkmcnt(2)
	v_mfma_f32_16x16x32_bf16 v[126:129], v[166:169], v[92:95], v[126:129]
	v_mfma_f32_16x16x32_bf16 v[122:125], v[166:169], v[68:71], v[122:125]
	ds_read_b128 v[162:165], v204 offset:128
	s_waitcnt lgkmcnt(2)
	v_mfma_f32_16x16x32_bf16 v[130:133], v[170:173], v[68:71], v[130:133]
	v_mfma_f32_16x16x32_bf16 v[134:137], v[170:173], v[92:95], v[134:137]
	ds_read_b128 v[166:169], v204 offset:6272
	s_waitcnt lgkmcnt(2)
	v_mfma_f32_16x16x32_bf16 v[142:145], v[174:177], v[92:95], v[142:145]
	v_mfma_f32_16x16x32_bf16 v[138:141], v[174:177], v[68:71], v[138:141]
	ds_read_b128 v[170:173], v204 offset:12416
	s_waitcnt lgkmcnt(2)
	v_mfma_f32_16x16x32_bf16 v[114:117], v[162:165], v[72:75], v[114:117]
	v_mfma_f32_16x16x32_bf16 v[118:121], v[162:165], v[96:99], v[118:121]
	ds_read_b128 v[174:177], v204 offset:18560
	s_waitcnt lgkmcnt(2)
	v_mfma_f32_16x16x32_bf16 v[126:129], v[166:169], v[96:99], v[126:129]
	v_mfma_f32_16x16x32_bf16 v[122:125], v[166:169], v[72:75], v[122:125]
	ds_read_b128 v[162:165], v205 offset:128
	s_waitcnt lgkmcnt(2)
	v_mfma_f32_16x16x32_bf16 v[130:133], v[170:173], v[72:75], v[130:133]
	v_mfma_f32_16x16x32_bf16 v[134:137], v[170:173], v[96:99], v[134:137]
	ds_read_b128 v[166:169], v205 offset:6272
	s_waitcnt lgkmcnt(2)
	v_mfma_f32_16x16x32_bf16 v[142:145], v[174:177], v[96:99], v[142:145]
	v_mfma_f32_16x16x32_bf16 v[138:141], v[174:177], v[72:75], v[138:141]
	ds_read_b128 v[170:173], v205 offset:12416
	s_waitcnt lgkmcnt(2)
	v_mfma_f32_16x16x32_bf16 v[114:117], v[162:165], v[76:79], v[114:117]
	v_mfma_f32_16x16x32_bf16 v[118:121], v[162:165], v[100:103], v[118:121]
	ds_read_b128 v[174:177], v205 offset:18560
	s_waitcnt lgkmcnt(2)
	v_mfma_f32_16x16x32_bf16 v[126:129], v[166:169], v[100:103], v[126:129]
	v_mfma_f32_16x16x32_bf16 v[122:125], v[166:169], v[76:79], v[122:125]
	ds_read_b128 v[162:165], v204 offset:256
	s_waitcnt lgkmcnt(2)
	v_mfma_f32_16x16x32_bf16 v[130:133], v[170:173], v[76:79], v[130:133]
	v_mfma_f32_16x16x32_bf16 v[134:137], v[170:173], v[100:103], v[134:137]
	ds_read_b128 v[166:169], v204 offset:6400
	s_waitcnt lgkmcnt(2)
	v_mfma_f32_16x16x32_bf16 v[142:145], v[174:177], v[100:103], v[142:145]
	v_mfma_f32_16x16x32_bf16 v[138:141], v[174:177], v[76:79], v[138:141]
	ds_read_b128 v[170:173], v204 offset:12544
	s_waitcnt lgkmcnt(2)
	v_mfma_f32_16x16x32_bf16 v[114:117], v[162:165], v[80:83], v[114:117]
	v_mfma_f32_16x16x32_bf16 v[118:121], v[162:165], v[104:107], v[118:121]
	ds_read_b128 v[174:177], v204 offset:18688
	s_waitcnt lgkmcnt(2)
	v_mfma_f32_16x16x32_bf16 v[126:129], v[166:169], v[104:107], v[126:129]
	v_mfma_f32_16x16x32_bf16 v[122:125], v[166:169], v[80:83], v[122:125]
	ds_read_b128 v[162:165], v205 offset:256
	s_waitcnt lgkmcnt(2)
	v_mfma_f32_16x16x32_bf16 v[130:133], v[170:173], v[80:83], v[130:133]
	v_mfma_f32_16x16x32_bf16 v[134:137], v[170:173], v[104:107], v[134:137]
	ds_read_b128 v[166:169], v205 offset:6400
	s_waitcnt lgkmcnt(2)
	v_mfma_f32_16x16x32_bf16 v[142:145], v[174:177], v[104:107], v[142:145]
	v_mfma_f32_16x16x32_bf16 v[138:141], v[174:177], v[80:83], v[138:141]
	ds_read_b128 v[170:173], v205 offset:12544
	s_waitcnt lgkmcnt(2)
	v_mfma_f32_16x16x32_bf16 v[114:117], v[162:165], v[84:87], v[114:117]
	v_mfma_f32_16x16x32_bf16 v[118:121], v[162:165], v[108:111], v[118:121]
	ds_read_b128 v[174:177], v205 offset:18688
	s_waitcnt lgkmcnt(2)
	v_mfma_f32_16x16x32_bf16 v[126:129], v[166:169], v[108:111], v[126:129]
	v_mfma_f32_16x16x32_bf16 v[122:125], v[166:169], v[84:87], v[122:125]
	s_waitcnt lgkmcnt(1)
	v_mfma_f32_16x16x32_bf16 v[130:133], v[170:173], v[84:87], v[130:133]
	v_mfma_f32_16x16x32_bf16 v[134:137], v[170:173], v[108:111], v[134:137]
	s_waitcnt lgkmcnt(0)
	v_mfma_f32_16x16x32_bf16 v[142:145], v[174:177], v[108:111], v[142:145]
	v_mfma_f32_16x16x32_bf16 v[138:141], v[174:177], v[84:87], v[138:141]
	ds_read_b64_tr_b16 v[162:163], v208 offset:16384
	ds_read_b64_tr_b16 v[164:165], v208 offset:20480
	ds_read_b64_tr_b16 v[166:167], v209 offset:16384
	ds_read_b64_tr_b16 v[168:169], v209 offset:20480
	ds_read_b64_tr_b16 v[170:171], v210 offset:16384
	ds_read_b64_tr_b16 v[172:173], v210 offset:20480
	s_nop 7
	v_max3_f32 v232, v114, v115, v116
	v_max_f32_e32 v232, v232, v117
	v_max3_f32 v233, v118, v119, v120
	v_max_f32_e32 v233, v233, v121
	v_max3_f32 v232, v232, v122, v123
	v_max3_f32 v232, v232, v124, v125
	v_max3_f32 v233, v233, v126, v127
	v_max3_f32 v233, v233, v128, v129
	v_max3_f32 v232, v232, v130, v131
	v_max3_f32 v232, v232, v132, v133
	v_max3_f32 v233, v233, v134, v135
	v_max3_f32 v233, v233, v136, v137
	v_max3_f32 v232, v232, v138, v139
	v_max3_f32 v232, v232, v140, v141
	v_max3_f32 v233, v233, v142, v143
	v_max3_f32 v233, v233, v144, v145
	v_max_f32_e32 v234, v232, v233
	v_cmp_ge_f32_e32 vcc, s38, v234
	s_cmp_eq_u64 vcc, exec
	s_cbranch_scc0 .Lat_rare_1
; __device__ __forceinline__ void finishSM(f32x16& p0, f32x16& p1, float alpha, float& l_reg, bf16x8& pa0, bf16x8& pa1, bf16x8& pa2, bf16x8& pa3) {
; #pragma unroll
;   for (int r = 0; r < 16; ++r) p1[r] = __builtin_amdgcn_exp2f(p1[r]);
;   float ps = 0;
; #pragma unroll
;   for (int r = 0; r < 16; ++r) ps += p0[r];
; #pragma unroll
;   for (int r = 0; r < 16; ++r) ps += p1[r];
;   { auto rr = __builtin_amdgcn_permlane32_swap(__float_as_uint(ps), __float_as_uint(ps), false, false);
;     ps = __uint_as_float(rr[0]) + __uint_as_float(rr[1]); }
;   l_reg = l_reg * alpha + ps;
;     ...
;   PK4(p0, 0, pa0); PK4(p0, 8, pa1); PK4(p1, 0, pa2); PK4(p1, 8, pa3);
;     ...
; }
; __device__ __forceinline__ void qkt(f32x16& p0, f32x16& p1, const char* Ks, const bf16x8* qr, const char* qL, int r32, int hi, float negm) {
; #pragma unroll
;   for (int r = 0; r < 16; ++r) { p0[r] = negm; p1[r] = negm; }
; #pragma unroll
;   for (int d0 = 0; d0 < 12; ++d0) { int cb = (d0 * 16 + hi * 8) * 2;
;     bf16x8 b0 = *reinterpret_cast<const bf16x8*>(Ks + KSWZ(r32, cb));
;     bf16x8 b1 = *reinterpret_cast<const bf16x8*>(Ks + KSWZ(32 + r32, cb));
;     const bf16x8 q = d0 < 8 ? qr[d0 < 8 ? d0 : 0] : *reinterpret_cast<const bf16x8*>(qL + (d0 - 8) * 1024);
;     p0 = __builtin_amdgcn_mfma_f32_32x32x16_bf16(b0, q, p0, 0, 0, 0);
;     p1 = __builtin_amdgcn_mfma_f32_32x32x16_bf16(b1, q, p1, 0, 0, 0); }
; }
; __device__ __forceinline__ int v_st(int k, int c) { const int kk = (k & ~0xC) | ((k & 4) << 1) | ((k & 8) >> 1); return ((kk >> 3) * 4 + (c >> 5)) * 512 + ((kk & 7) * 32 + (c & 31)) * 2; }
; __device__ __forceinline__ int v_rd_base(int lane) { return ((lane & 3) << 3) | (((lane >> 2) & 3) << 6) | (((lane >> 4) & 1) << 5) | (((lane >> 5) & 1) << 8); }
; template <int OFF> __device__ __forceinline__ s16x4 tr_read(int vb) {
;   s16x4 r; asm volatile("ds_read_b64_tr_b16 %0, %1 offset:%2" : "=&v"(r) : "v"(vb), "i"(OFF) : "memory"); return r;
; }
; template <int D0> __device__ __forceinline__ void pv_one(f32x16& od, int vb, bf16x8 pa0, bf16x8 pa1, bf16x8 pa2, bf16x8 pa3) {
;   const s16x4 l0 = tr_read<v_rd_off(D0, 0, 0)>(vb), h0 = tr_read<v_rd_off(D0, 0, 1)>(vb), l1 = tr_read<v_rd_off(D0, 1, 0)>(vb), h1 = tr_read<v_rd_off(D0, 1, 1)>(vb);
;   const s16x4 l2 = tr_read<v_rd_off(D0, 2, 0)>(vb), h2 = tr_read<v_rd_off(D0, 2, 1)>(vb), l3 = tr_read<v_rd_off(D0, 3, 0)>(vb), h3 = tr_read<v_rd_off(D0, 3, 1)>(vb);
.Lat_cont_1:
	v_exp_f32_e32 v114, v114
	v_exp_f32_e32 v115, v115
	v_exp_f32_e32 v116, v116
	v_exp_f32_e32 v117, v117
	v_add_f32_e32 v220, v220, v114
	v_add_f32_e32 v220, v220, v115
	v_add_f32_e32 v220, v220, v116
	v_add_f32_e32 v220, v220, v117
	v_exp_f32_e32 v122, v122
	v_exp_f32_e32 v123, v123
	v_exp_f32_e32 v124, v124
	v_exp_f32_e32 v125, v125
	v_add_f32_e32 v220, v220, v122
	v_add_f32_e32 v220, v220, v123
	v_add_f32_e32 v220, v220, v124
	v_add_f32_e32 v220, v220, v125
	v_cvt_pk_bf16_f32 v146, v114, v115
	v_cvt_pk_bf16_f32 v147, v116, v117
	v_cvt_pk_bf16_f32 v148, v122, v123
	v_cvt_pk_bf16_f32 v149, v124, v125
	v_exp_f32_e32 v118, v118
	v_exp_f32_e32 v119, v119
	v_exp_f32_e32 v120, v120
	v_exp_f32_e32 v121, v121
	v_add_f32_e32 v221, v221, v118
	v_add_f32_e32 v221, v221, v119
	v_add_f32_e32 v221, v221, v120
	v_add_f32_e32 v221, v221, v121
	v_exp_f32_e32 v126, v126
	v_exp_f32_e32 v127, v127
	v_exp_f32_e32 v128, v128
	v_exp_f32_e32 v129, v129
	v_add_f32_e32 v221, v221, v126
	v_add_f32_e32 v221, v221, v127
	v_add_f32_e32 v221, v221, v128
	v_add_f32_e32 v221, v221, v129
	v_cvt_pk_bf16_f32 v154, v118, v119
	v_cvt_pk_bf16_f32 v155, v120, v121
	v_cvt_pk_bf16_f32 v156, v126, v127
	v_cvt_pk_bf16_f32 v157, v128, v129
	s_nop 1
	s_waitcnt lgkmcnt(4)
	v_mfma_f32_16x16x32_bf16 v[0:3], v[146:149], v[162:165], v[0:3]
	v_mfma_f32_16x16x32_bf16 v[32:35], v[154:157], v[162:165], v[32:35]
	ds_read_b64_tr_b16 v[174:175], v211 offset:16384
	ds_read_b64_tr_b16 v[176:177], v211 offset:20480
	v_exp_f32_e32 v130, v130
	v_exp_f32_e32 v131, v131
	v_exp_f32_e32 v132, v132
	v_exp_f32_e32 v133, v133
	v_add_f32_e32 v220, v220, v130
	s_waitcnt lgkmcnt(4)
	v_mfma_f32_16x16x32_bf16 v[36:39], v[154:157], v[166:169], v[36:39]
	v_mfma_f32_16x16x32_bf16 v[4:7], v[146:149], v[166:169], v[4:7]
	ds_read_b64_tr_b16 v[162:163], v212 offset:16384
	ds_read_b64_tr_b16 v[164:165], v212 offset:20480
	v_add_f32_e32 v220, v220, v131
	v_add_f32_e32 v220, v220, v132
	v_add_f32_e32 v220, v220, v133
	v_exp_f32_e32 v138, v138
	v_exp_f32_e32 v139, v139
	s_waitcnt lgkmcnt(4)
	v_mfma_f32_16x16x32_bf16 v[8:11], v[146:149], v[170:173], v[8:11]
	v_mfma_f32_16x16x32_bf16 v[40:43], v[154:157], v[170:173], v[40:43]
	ds_read_b64_tr_b16 v[166:167], v213 offset:16384
	ds_read_b64_tr_b16 v[168:169], v213 offset:20480
	v_exp_f32_e32 v140, v140
	v_exp_f32_e32 v141, v141
	v_add_f32_e32 v220, v220, v138
	v_add_f32_e32 v220, v220, v139
	v_add_f32_e32 v220, v220, v140
	s_waitcnt lgkmcnt(4)
	v_mfma_f32_16x16x32_bf16 v[44:47], v[154:157], v[174:177], v[44:47]
	v_mfma_f32_16x16x32_bf16 v[12:15], v[146:149], v[174:177], v[12:15]
	ds_read_b64_tr_b16 v[170:171], v214 offset:16384
	ds_read_b64_tr_b16 v[172:173], v214 offset:20480
	v_add_f32_e32 v220, v220, v141
	v_cvt_pk_bf16_f32 v150, v130, v131
	v_cvt_pk_bf16_f32 v151, v132, v133
	v_cvt_pk_bf16_f32 v152, v138, v139
	v_cvt_pk_bf16_f32 v153, v140, v141
	s_waitcnt lgkmcnt(4)
	v_mfma_f32_16x16x32_bf16 v[16:19], v[146:149], v[162:165], v[16:19]
	v_mfma_f32_16x16x32_bf16 v[48:51], v[154:157], v[162:165], v[48:51]
	ds_read_b64_tr_b16 v[174:175], v215 offset:16384
	ds_read_b64_tr_b16 v[176:177], v215 offset:20480
	v_exp_f32_e32 v134, v134
	v_exp_f32_e32 v135, v135
	v_exp_f32_e32 v136, v136
	v_exp_f32_e32 v137, v137
	v_add_f32_e32 v221, v221, v134
	s_waitcnt lgkmcnt(4)
	v_mfma_f32_16x16x32_bf16 v[52:55], v[154:157], v[166:169], v[52:55]
	v_mfma_f32_16x16x32_bf16 v[20:23], v[146:149], v[166:169], v[20:23]
	ds_read_b64_tr_b16 v[162:163], v208 offset:24576
	ds_read_b64_tr_b16 v[164:165], v208 offset:28672
	v_add_f32_e32 v221, v221, v135
	v_add_f32_e32 v221, v221, v136
	v_add_f32_e32 v221, v221, v137
	v_exp_f32_e32 v142, v142
	v_exp_f32_e32 v143, v143
	s_waitcnt lgkmcnt(4)
	v_mfma_f32_16x16x32_bf16 v[24:27], v[146:149], v[170:173], v[24:27]
	v_mfma_f32_16x16x32_bf16 v[56:59], v[154:157], v[170:173], v[56:59]
	ds_read_b64_tr_b16 v[166:167], v209 offset:24576
	ds_read_b64_tr_b16 v[168:169], v209 offset:28672
	v_exp_f32_e32 v144, v144
	v_exp_f32_e32 v145, v145
	v_add_f32_e32 v221, v221, v142
	v_add_f32_e32 v221, v221, v143
	v_add_f32_e32 v221, v221, v144
	s_waitcnt lgkmcnt(4)
	v_mfma_f32_16x16x32_bf16 v[60:63], v[154:157], v[174:177], v[60:63]
	v_mfma_f32_16x16x32_bf16 v[28:31], v[146:149], v[174:177], v[28:31]
	ds_read_b64_tr_b16 v[170:171], v210 offset:24576
	ds_read_b64_tr_b16 v[172:173], v210 offset:28672
	v_add_f32_e32 v221, v221, v145
	v_cvt_pk_bf16_f32 v158, v134, v135
	v_cvt_pk_bf16_f32 v159, v136, v137
	v_cvt_pk_bf16_f32 v160, v142, v143
	v_cvt_pk_bf16_f32 v161, v144, v145
	s_waitcnt lgkmcnt(4)
	s_nop 1
	v_mfma_f32_16x16x32_bf16 v[0:3], v[150:153], v[162:165], v[0:3]
	v_mfma_f32_16x16x32_bf16 v[32:35], v[158:161], v[162:165], v[32:35]
	ds_read_b64_tr_b16 v[174:175], v211 offset:24576
	ds_read_b64_tr_b16 v[176:177], v211 offset:28672
	s_waitcnt lgkmcnt(4)
	v_mfma_f32_16x16x32_bf16 v[36:39], v[158:161], v[166:169], v[36:39]
	v_mfma_f32_16x16x32_bf16 v[4:7], v[150:153], v[166:169], v[4:7]
	ds_read_b64_tr_b16 v[162:163], v212 offset:24576
	ds_read_b64_tr_b16 v[164:165], v212 offset:28672
	s_waitcnt lgkmcnt(4)
	v_mfma_f32_16x16x32_bf16 v[8:11], v[150:153], v[170:173], v[8:11]
	v_mfma_f32_16x16x32_bf16 v[40:43], v[158:161], v[170:173], v[40:43]
	ds_read_b64_tr_b16 v[166:167], v213 offset:24576
	ds_read_b64_tr_b16 v[168:169], v213 offset:28672
	s_waitcnt lgkmcnt(4)
	v_mfma_f32_16x16x32_bf16 v[44:47], v[158:161], v[174:177], v[44:47]
	v_mfma_f32_16x16x32_bf16 v[12:15], v[150:153], v[174:177], v[12:15]
	ds_read_b64_tr_b16 v[170:171], v214 offset:24576
	ds_read_b64_tr_b16 v[172:173], v214 offset:28672
	s_waitcnt lgkmcnt(4)
	v_mfma_f32_16x16x32_bf16 v[16:19], v[150:153], v[162:165], v[16:19]
	v_mfma_f32_16x16x32_bf16 v[48:51], v[158:161], v[162:165], v[48:51]
	ds_read_b64_tr_b16 v[174:175], v215 offset:24576
	ds_read_b64_tr_b16 v[176:177], v215 offset:28672
	s_waitcnt lgkmcnt(4)
	v_mfma_f32_16x16x32_bf16 v[52:55], v[158:161], v[166:169], v[52:55]
	v_mfma_f32_16x16x32_bf16 v[20:23], v[150:153], v[166:169], v[20:23]
	s_waitcnt lgkmcnt(2)
	v_mfma_f32_16x16x32_bf16 v[24:27], v[150:153], v[170:173], v[24:27]
	v_mfma_f32_16x16x32_bf16 v[56:59], v[158:161], v[170:173], v[56:59]
	s_waitcnt lgkmcnt(0)
	v_mfma_f32_16x16x32_bf16 v[60:63], v[158:161], v[174:177], v[60:63]
	v_mfma_f32_16x16x32_bf16 v[28:31], v[150:153], v[174:177], v[28:31]
	s_waitcnt vmcnt(5)
	s_barrier
; #define SBAR() __builtin_amdgcn_sched_barrier(0)
; #define SLOAD(i, k0) do { sr_[i].vs0 = *(const bf16x8*)(&Vh[(long)((k0) + sr) * 128 + sc]); sr_[i].vs1 = *(const bf16x8*)(&Vh[(long)((k0) + 32 + sr) * 128 + sc]); \
;     sr_[i].ks0 = *(const bf16x8*)(&Kn[(long)((k0) + sr) * 128 + sc]); sr_[i].ks1 = *(const bf16x8*)(&Kn[(long)((k0) + 32 + sr) * 128 + sc]); \
;     sr_[i].ks2 = *(const bf16x8*)(&Kr[(long)((k0) + rr) * 64 + rc]); } while (0)
; __device__ __forceinline__ void qkt(f32x16& p0, f32x16& p1, const char* Ks, const bf16x8* qr, const char* qL, int r32, int hi, float negm) {
; #pragma unroll
;   for (int r = 0; r < 16; ++r) { p0[r] = negm; p1[r] = negm; }
; #pragma unroll
;   for (int d0 = 0; d0 < 12; ++d0) { int cb = (d0 * 16 + hi * 8) * 2;
;     bf16x8 b0 = *reinterpret_cast<const bf16x8*>(Ks + KSWZ(r32, cb));
;     bf16x8 b1 = *reinterpret_cast<const bf16x8*>(Ks + KSWZ(32 + r32, cb));
;     const bf16x8 q = d0 < 8 ? qr[d0 < 8 ? d0 : 0] : *reinterpret_cast<const bf16x8*>(qL + (d0 - 8) * 1024);
;     p0 = __builtin_amdgcn_mfma_f32_32x32x16_bf16(b0, q, p0, 0, 0, 0);
;     p1 = __builtin_amdgcn_mfma_f32_32x32x16_bf16(b1, q, p1, 0, 0, 0); }
; }
; __device__ __forceinline__ void attn_unit(const bf16_t* __restrict__ Qb, const bf16_t* __restrict__ Kn, const bf16_t* __restrict__ Kr, const bf16_t* __restrict__ Vh,
;                                           bf16_t* __restrict__ Ob, char* lds) {
;     ...
;     SBAR(); qkt(pA0, pA1, K_lds, qr, qL, r32, hi, -m_reg);
;     finishSM(pB0, pB1, alB, l_reg, pa0, pa1, pa2, pa3); SBAR();
;     if (SDEPTH == 1 || j + 3 < NT) SLOAD(SE, (j + 1 + SDEPTH) * KVBLK); SBAR();
;     pv_d0(o, vb0 + (int)SHM_V, pa0, pa1, pa2, pa3); partialSM<false>(pA0, pA1, m_reg, alA);
	s_add_i32 m0, s43, 73728
	s_nop 0
	global_load_lds_dwordx4 v[178:179], off
	s_add_i32 m0, s43, 81920
	s_nop 0
	global_load_lds_dwordx4 v[180:181], off
	s_add_i32 m0, s43, 90112
	s_nop 0
	global_load_lds_dwordx4 v[182:183], off
	s_add_i32 m0, s43, 16384
	s_nop 0
	global_load_lds_dwordx4 v[184:185], off
	s_add_i32 m0, s43, 24576
	s_nop 0
	global_load_lds_dwordx4 v[186:187], off
	v_lshl_add_u64 v[178:179], v[178:179], 0, v[188:189]
	v_lshl_add_u64 v[180:181], v[180:181], 0, v[190:191]
	v_lshl_add_u64 v[182:183], v[182:183], 0, v[192:193]
	v_lshl_add_u64 v[184:185], v[184:185], 0, s[22:23]
	v_lshl_add_u64 v[186:187], v[186:187], 0, s[22:23]
	ds_read_b128 v[162:165], v206 offset:0
	ds_read_b128 v[166:169], v206 offset:6144
	ds_read_b128 v[170:173], v206 offset:12288
	s_waitcnt lgkmcnt(2)
	v_mfma_f32_16x16x32_bf16 v[114:117], v[162:165], v[64:67], v[224:227]
	v_mfma_f32_16x16x32_bf16 v[118:121], v[162:165], v[88:91], v[228:231]
	ds_read_b128 v[174:177], v206 offset:18432
	s_waitcnt lgkmcnt(2)
	v_mfma_f32_16x16x32_bf16 v[126:129], v[166:169], v[88:91], v[228:231]
	v_mfma_f32_16x16x32_bf16 v[122:125], v[166:169], v[64:67], v[224:227]
	ds_read_b128 v[162:165], v207 offset:0
	s_waitcnt lgkmcnt(2)
	v_mfma_f32_16x16x32_bf16 v[130:133], v[170:173], v[64:67], v[224:227]
	v_mfma_f32_16x16x32_bf16 v[134:137], v[170:173], v[88:91], v[228:231]
	ds_read_b128 v[166:169], v207 offset:6144
	s_waitcnt lgkmcnt(2)
	v_mfma_f32_16x16x32_bf16 v[142:145], v[174:177], v[88:91], v[228:231]
	v_mfma_f32_16x16x32_bf16 v[138:141], v[174:177], v[64:67], v[224:227]
	ds_read_b128 v[170:173], v207 offset:12288
	s_waitcnt lgkmcnt(2)
	v_mfma_f32_16x16x32_bf16 v[114:117], v[162:165], v[68:71], v[114:117]
	v_mfma_f32_16x16x32_bf16 v[118:121], v[162:165], v[92:95], v[118:121]
	ds_read_b128 v[174:177], v207 offset:18432
	s_waitcnt lgkmcnt(2)
	v_mfma_f32_16x16x32_bf16 v[126:129], v[166:169], v[92:95], v[126:129]
	v_mfma_f32_16x16x32_bf16 v[122:125], v[166:169], v[68:71], v[122:125]
	ds_read_b128 v[162:165], v206 offset:128
	s_waitcnt lgkmcnt(2)
	v_mfma_f32_16x16x32_bf16 v[130:133], v[170:173], v[68:71], v[130:133]
	v_mfma_f32_16x16x32_bf16 v[134:137], v[170:173], v[92:95], v[134:137]
	ds_read_b128 v[166:169], v206 offset:6272
	s_waitcnt lgkmcnt(2)
	v_mfma_f32_16x16x32_bf16 v[142:145], v[174:177], v[92:95], v[142:145]
	v_mfma_f32_16x16x32_bf16 v[138:141], v[174:177], v[68:71], v[138:141]
	ds_read_b128 v[170:173], v206 offset:12416
	s_waitcnt lgkmcnt(2)
	v_mfma_f32_16x16x32_bf16 v[114:117], v[162:165], v[72:75], v[114:117]
	v_mfma_f32_16x16x32_bf16 v[118:121], v[162:165], v[96:99], v[118:121]
	ds_read_b128 v[174:177], v206 offset:18560
	s_waitcnt lgkmcnt(2)
	v_mfma_f32_16x16x32_bf16 v[126:129], v[166:169], v[96:99], v[126:129]
	v_mfma_f32_16x16x32_bf16 v[122:125], v[166:169], v[72:75], v[122:125]
	ds_read_b128 v[162:165], v207 offset:128
	s_waitcnt lgkmcnt(2)
	v_mfma_f32_16x16x32_bf16 v[130:133], v[170:173], v[72:75], v[130:133]
	v_mfma_f32_16x16x32_bf16 v[134:137], v[170:173], v[96:99], v[134:137]
	ds_read_b128 v[166:169], v207 offset:6272
	s_waitcnt lgkmcnt(2)
	v_mfma_f32_16x16x32_bf16 v[142:145], v[174:177], v[96:99], v[142:145]
	v_mfma_f32_16x16x32_bf16 v[138:141], v[174:177], v[72:75], v[138:141]
	ds_read_b128 v[170:173], v207 offset:12416
	s_waitcnt lgkmcnt(2)
	v_mfma_f32_16x16x32_bf16 v[114:117], v[162:165], v[76:79], v[114:117]
	v_mfma_f32_16x16x32_bf16 v[118:121], v[162:165], v[100:103], v[118:121]
	ds_read_b128 v[174:177], v207 offset:18560
	s_waitcnt lgkmcnt(2)
	v_mfma_f32_16x16x32_bf16 v[126:129], v[166:169], v[100:103], v[126:129]
	v_mfma_f32_16x16x32_bf16 v[122:125], v[166:169], v[76:79], v[122:125]
	ds_read_b128 v[162:165], v206 offset:256
	s_waitcnt lgkmcnt(2)
	v_mfma_f32_16x16x32_bf16 v[130:133], v[170:173], v[76:79], v[130:133]
	v_mfma_f32_16x16x32_bf16 v[134:137], v[170:173], v[100:103], v[134:137]
	ds_read_b128 v[166:169], v206 offset:6400
	s_waitcnt lgkmcnt(2)
	v_mfma_f32_16x16x32_bf16 v[142:145], v[174:177], v[100:103], v[142:145]
	v_mfma_f32_16x16x32_bf16 v[138:141], v[174:177], v[76:79], v[138:141]
	ds_read_b128 v[170:173], v206 offset:12544
	s_waitcnt lgkmcnt(2)
	v_mfma_f32_16x16x32_bf16 v[114:117], v[162:165], v[80:83], v[114:117]
	v_mfma_f32_16x16x32_bf16 v[118:121], v[162:165], v[104:107], v[118:121]
	ds_read_b128 v[174:177], v206 offset:18688
	s_waitcnt lgkmcnt(2)
	v_mfma_f32_16x16x32_bf16 v[126:129], v[166:169], v[104:107], v[126:129]
	v_mfma_f32_16x16x32_bf16 v[122:125], v[166:169], v[80:83], v[122:125]
	ds_read_b128 v[162:165], v207 offset:256
	s_waitcnt lgkmcnt(2)
	v_mfma_f32_16x16x32_bf16 v[130:133], v[170:173], v[80:83], v[130:133]
	v_mfma_f32_16x16x32_bf16 v[134:137], v[170:173], v[104:107], v[134:137]
	ds_read_b128 v[166:169], v207 offset:6400
	s_waitcnt lgkmcnt(2)
	v_mfma_f32_16x16x32_bf16 v[142:145], v[174:177], v[104:107], v[142:145]
	v_mfma_f32_16x16x32_bf16 v[138:141], v[174:177], v[80:83], v[138:141]
	ds_read_b128 v[170:173], v207 offset:12544
	s_waitcnt lgkmcnt(2)
	v_mfma_f32_16x16x32_bf16 v[114:117], v[162:165], v[84:87], v[114:117]
	v_mfma_f32_16x16x32_bf16 v[118:121], v[162:165], v[108:111], v[118:121]
	ds_read_b128 v[174:177], v207 offset:18688
	s_waitcnt lgkmcnt(2)
	v_mfma_f32_16x16x32_bf16 v[126:129], v[166:169], v[108:111], v[126:129]
	v_mfma_f32_16x16x32_bf16 v[122:125], v[166:169], v[84:87], v[122:125]
	s_waitcnt lgkmcnt(1)
	v_mfma_f32_16x16x32_bf16 v[130:133], v[170:173], v[84:87], v[130:133]
	v_mfma_f32_16x16x32_bf16 v[134:137], v[170:173], v[108:111], v[134:137]
	s_waitcnt lgkmcnt(0)
	v_mfma_f32_16x16x32_bf16 v[142:145], v[174:177], v[108:111], v[142:145]
	v_mfma_f32_16x16x32_bf16 v[138:141], v[174:177], v[84:87], v[138:141]
	ds_read_b64_tr_b16 v[162:163], v208 offset:32768
	ds_read_b64_tr_b16 v[164:165], v208 offset:36864
	ds_read_b64_tr_b16 v[166:167], v209 offset:32768
	ds_read_b64_tr_b16 v[168:169], v209 offset:36864
	ds_read_b64_tr_b16 v[170:171], v210 offset:32768
	ds_read_b64_tr_b16 v[172:173], v210 offset:36864
	s_nop 7
	v_max3_f32 v232, v114, v115, v116
	v_max_f32_e32 v232, v232, v117
	v_max3_f32 v233, v118, v119, v120
	v_max_f32_e32 v233, v233, v121
	v_max3_f32 v232, v232, v122, v123
	v_max3_f32 v232, v232, v124, v125
	v_max3_f32 v233, v233, v126, v127
	v_max3_f32 v233, v233, v128, v129
	v_max3_f32 v232, v232, v130, v131
	v_max3_f32 v232, v232, v132, v133
	v_max3_f32 v233, v233, v134, v135
	v_max3_f32 v233, v233, v136, v137
	v_max3_f32 v232, v232, v138, v139
	v_max3_f32 v232, v232, v140, v141
	v_max3_f32 v233, v233, v142, v143
	v_max3_f32 v233, v233, v144, v145
	v_max_f32_e32 v234, v232, v233
	v_cmp_ge_f32_e32 vcc, s38, v234
	s_cmp_eq_u64 vcc, exec
	s_cbranch_scc0 .Lat_rare_2
; __device__ __forceinline__ void finishSM(f32x16& p0, f32x16& p1, float alpha, float& l_reg, bf16x8& pa0, bf16x8& pa1, bf16x8& pa2, bf16x8& pa3) {
; #pragma unroll
;   for (int r = 0; r < 16; ++r) p1[r] = __builtin_amdgcn_exp2f(p1[r]);
;   float ps = 0;
; #pragma unroll
;   for (int r = 0; r < 16; ++r) ps += p0[r];
; #pragma unroll
;   for (int r = 0; r < 16; ++r) ps += p1[r];
;   { auto rr = __builtin_amdgcn_permlane32_swap(__float_as_uint(ps), __float_as_uint(ps), false, false);
;     ps = __uint_as_float(rr[0]) + __uint_as_float(rr[1]); }
;   l_reg = l_reg * alpha + ps;
;     ...
;   PK4(p0, 0, pa0); PK4(p0, 8, pa1); PK4(p1, 0, pa2); PK4(p1, 8, pa3);
;     ...
; }
; __device__ __forceinline__ void qkt(f32x16& p0, f32x16& p1, const char* Ks, const bf16x8* qr, const char* qL, int r32, int hi, float negm) {
; #pragma unroll
;   for (int r = 0; r < 16; ++r) { p0[r] = negm; p1[r] = negm; }
; #pragma unroll
;   for (int d0 = 0; d0 < 12; ++d0) { int cb = (d0 * 16 + hi * 8) * 2;
;     bf16x8 b0 = *reinterpret_cast<const bf16x8*>(Ks + KSWZ(r32, cb));
;     bf16x8 b1 = *reinterpret_cast<const bf16x8*>(Ks + KSWZ(32 + r32, cb));
;     const bf16x8 q = d0 < 8 ? qr[d0 < 8 ? d0 : 0] : *reinterpret_cast<const bf16x8*>(qL + (d0 - 8) * 1024);
;     p0 = __builtin_amdgcn_mfma_f32_32x32x16_bf16(b0, q, p0, 0, 0, 0);
;     p1 = __builtin_amdgcn_mfma_f32_32x32x16_bf16(b1, q, p1, 0, 0, 0); }
; }
; __device__ __forceinline__ int v_st(int k, int c) { const int kk = (k & ~0xC) | ((k & 4) << 1) | ((k & 8) >> 1); return ((kk >> 3) * 4 + (c >> 5)) * 512 + ((kk & 7) * 32 + (c & 31)) * 2; }
; __device__ __forceinline__ int v_rd_base(int lane) { return ((lane & 3) << 3) | (((lane >> 2) & 3) << 6) | (((lane >> 4) & 1) << 5) | (((lane >> 5) & 1) << 8); }
; template <int OFF> __device__ __forceinline__ s16x4 tr_read(int vb) {
;   s16x4 r; asm volatile("ds_read_b64_tr_b16 %0, %1 offset:%2" : "=&v"(r) : "v"(vb), "i"(OFF) : "memory"); return r;
; }
; template <int D0> __device__ __forceinline__ void pv_one(f32x16& od, int vb, bf16x8 pa0, bf16x8 pa1, bf16x8 pa2, bf16x8 pa3) {
;   const s16x4 l0 = tr_read<v_rd_off(D0, 0, 0)>(vb), h0 = tr_read<v_rd_off(D0, 0, 1)>(vb), l1 = tr_read<v_rd_off(D0, 1, 0)>(vb), h1 = tr_read<v_rd_off(D0, 1, 1)>(vb);
;   const s16x4 l2 = tr_read<v_rd_off(D0, 2, 0)>(vb), h2 = tr_read<v_rd_off(D0, 2, 1)>(vb), l3 = tr_read<v_rd_off(D0, 3, 0)>(vb), h3 = tr_read<v_rd_off(D0, 3, 1)>(vb);
.Lat_cont_2:
	v_exp_f32_e32 v114, v114
	v_exp_f32_e32 v115, v115
	v_exp_f32_e32 v116, v116
	v_exp_f32_e32 v117, v117
	v_add_f32_e32 v220, v220, v114
	v_add_f32_e32 v220, v220, v115
	v_add_f32_e32 v220, v220, v116
	v_add_f32_e32 v220, v220, v117
	v_exp_f32_e32 v122, v122
	v_exp_f32_e32 v123, v123
	v_exp_f32_e32 v124, v124
	v_exp_f32_e32 v125, v125
	v_add_f32_e32 v220, v220, v122
	v_add_f32_e32 v220, v220, v123
	v_add_f32_e32 v220, v220, v124
	v_add_f32_e32 v220, v220, v125
	v_cvt_pk_bf16_f32 v146, v114, v115
	v_cvt_pk_bf16_f32 v147, v116, v117
	v_cvt_pk_bf16_f32 v148, v122, v123
	v_cvt_pk_bf16_f32 v149, v124, v125
	v_exp_f32_e32 v118, v118
	v_exp_f32_e32 v119, v119
	v_exp_f32_e32 v120, v120
	v_exp_f32_e32 v121, v121
	v_add_f32_e32 v221, v221, v118
	v_add_f32_e32 v221, v221, v119
	v_add_f32_e32 v221, v221, v120
	v_add_f32_e32 v221, v221, v121
	v_exp_f32_e32 v126, v126
	v_exp_f32_e32 v127, v127
	v_exp_f32_e32 v128, v128
	v_exp_f32_e32 v129, v129
	v_add_f32_e32 v221, v221, v126
	v_add_f32_e32 v221, v221, v127
	v_add_f32_e32 v221, v221, v128
	v_add_f32_e32 v221, v221, v129
	v_cvt_pk_bf16_f32 v154, v118, v119
	v_cvt_pk_bf16_f32 v155, v120, v121
	v_cvt_pk_bf16_f32 v156, v126, v127
	v_cvt_pk_bf16_f32 v157, v128, v129
	s_nop 1
	s_waitcnt lgkmcnt(4)
	v_mfma_f32_16x16x32_bf16 v[0:3], v[146:149], v[162:165], v[0:3]
	v_mfma_f32_16x16x32_bf16 v[32:35], v[154:157], v[162:165], v[32:35]
	ds_read_b64_tr_b16 v[174:175], v211 offset:32768
	ds_read_b64_tr_b16 v[176:177], v211 offset:36864
	v_exp_f32_e32 v130, v130
	v_exp_f32_e32 v131, v131
	v_exp_f32_e32 v132, v132
	v_exp_f32_e32 v133, v133
	v_add_f32_e32 v220, v220, v130
	s_waitcnt lgkmcnt(4)
	v_mfma_f32_16x16x32_bf16 v[36:39], v[154:157], v[166:169], v[36:39]
	v_mfma_f32_16x16x32_bf16 v[4:7], v[146:149], v[166:169], v[4:7]
	ds_read_b64_tr_b16 v[162:163], v212 offset:32768
	ds_read_b64_tr_b16 v[164:165], v212 offset:36864
	v_add_f32_e32 v220, v220, v131
	v_add_f32_e32 v220, v220, v132
	v_add_f32_e32 v220, v220, v133
	v_exp_f32_e32 v138, v138
	v_exp_f32_e32 v139, v139
	s_waitcnt lgkmcnt(4)
	v_mfma_f32_16x16x32_bf16 v[8:11], v[146:149], v[170:173], v[8:11]
	v_mfma_f32_16x16x32_bf16 v[40:43], v[154:157], v[170:173], v[40:43]
	ds_read_b64_tr_b16 v[166:167], v213 offset:32768
	ds_read_b64_tr_b16 v[168:169], v213 offset:36864
	v_exp_f32_e32 v140, v140
	v_exp_f32_e32 v141, v141
	v_add_f32_e32 v220, v220, v138
	v_add_f32_e32 v220, v220, v139
	v_add_f32_e32 v220, v220, v140
	s_waitcnt lgkmcnt(4)
	v_mfma_f32_16x16x32_bf16 v[44:47], v[154:157], v[174:177], v[44:47]
	v_mfma_f32_16x16x32_bf16 v[12:15], v[146:149], v[174:177], v[12:15]
	ds_read_b64_tr_b16 v[170:171], v214 offset:32768
	ds_read_b64_tr_b16 v[172:173], v214 offset:36864
	v_add_f32_e32 v220, v220, v141
	v_cvt_pk_bf16_f32 v150, v130, v131
	v_cvt_pk_bf16_f32 v151, v132, v133
	v_cvt_pk_bf16_f32 v152, v138, v139
	v_cvt_pk_bf16_f32 v153, v140, v141
	s_waitcnt lgkmcnt(4)
	v_mfma_f32_16x16x32_bf16 v[16:19], v[146:149], v[162:165], v[16:19]
	v_mfma_f32_16x16x32_bf16 v[48:51], v[154:157], v[162:165], v[48:51]
	ds_read_b64_tr_b16 v[174:175], v215 offset:32768
	ds_read_b64_tr_b16 v[176:177], v215 offset:36864
	v_exp_f32_e32 v134, v134
	v_exp_f32_e32 v135, v135
	v_exp_f32_e32 v136, v136
	v_exp_f32_e32 v137, v137
	v_add_f32_e32 v221, v221, v134
	s_waitcnt lgkmcnt(4)
	v_mfma_f32_16x16x32_bf16 v[52:55], v[154:157], v[166:169], v[52:55]
	v_mfma_f32_16x16x32_bf16 v[20:23], v[146:149], v[166:169], v[20:23]
	ds_read_b64_tr_b16 v[162:163], v208 offset:40960
	ds_read_b64_tr_b16 v[164:165], v208 offset:45056
	v_add_f32_e32 v221, v221, v135
	v_add_f32_e32 v221, v221, v136
	v_add_f32_e32 v221, v221, v137
	v_exp_f32_e32 v142, v142
	v_exp_f32_e32 v143, v143
	s_waitcnt lgkmcnt(4)
	v_mfma_f32_16x16x32_bf16 v[24:27], v[146:149], v[170:173], v[24:27]
	v_mfma_f32_16x16x32_bf16 v[56:59], v[154:157], v[170:173], v[56:59]
	ds_read_b64_tr_b16 v[166:167], v209 offset:40960
	ds_read_b64_tr_b16 v[168:169], v209 offset:45056
	v_exp_f32_e32 v144, v144
	v_exp_f32_e32 v145, v145
	v_add_f32_e32 v221, v221, v142
	v_add_f32_e32 v221, v221, v143
	v_add_f32_e32 v221, v221, v144
	s_waitcnt lgkmcnt(4)
	v_mfma_f32_16x16x32_bf16 v[60:63], v[154:157], v[174:177], v[60:63]
	v_mfma_f32_16x16x32_bf16 v[28:31], v[146:149], v[174:177], v[28:31]
	ds_read_b64_tr_b16 v[170:171], v210 offset:40960
	ds_read_b64_tr_b16 v[172:173], v210 offset:45056
	v_add_f32_e32 v221, v221, v145
	v_cvt_pk_bf16_f32 v158, v134, v135
	v_cvt_pk_bf16_f32 v159, v136, v137
	v_cvt_pk_bf16_f32 v160, v142, v143
	v_cvt_pk_bf16_f32 v161, v144, v145
	s_waitcnt lgkmcnt(4)
	s_nop 1
	v_mfma_f32_16x16x32_bf16 v[0:3], v[150:153], v[162:165], v[0:3]
	v_mfma_f32_16x16x32_bf16 v[32:35], v[158:161], v[162:165], v[32:35]
	ds_read_b64_tr_b16 v[174:175], v211 offset:40960
	ds_read_b64_tr_b16 v[176:177], v211 offset:45056
	s_waitcnt lgkmcnt(4)
	v_mfma_f32_16x16x32_bf16 v[36:39], v[158:161], v[166:169], v[36:39]
	v_mfma_f32_16x16x32_bf16 v[4:7], v[150:153], v[166:169], v[4:7]
	ds_read_b64_tr_b16 v[162:163], v212 offset:40960
	ds_read_b64_tr_b16 v[164:165], v212 offset:45056
	s_waitcnt lgkmcnt(4)
	v_mfma_f32_16x16x32_bf16 v[8:11], v[150:153], v[170:173], v[8:11]
	v_mfma_f32_16x16x32_bf16 v[40:43], v[158:161], v[170:173], v[40:43]
	ds_read_b64_tr_b16 v[166:167], v213 offset:40960
	ds_read_b64_tr_b16 v[168:169], v213 offset:45056
	s_waitcnt lgkmcnt(4)
	v_mfma_f32_16x16x32_bf16 v[44:47], v[158:161], v[174:177], v[44:47]
	v_mfma_f32_16x16x32_bf16 v[12:15], v[150:153], v[174:177], v[12:15]
	ds_read_b64_tr_b16 v[170:171], v214 offset:40960
	ds_read_b64_tr_b16 v[172:173], v214 offset:45056
	s_waitcnt lgkmcnt(4)
	v_mfma_f32_16x16x32_bf16 v[16:19], v[150:153], v[162:165], v[16:19]
	v_mfma_f32_16x16x32_bf16 v[48:51], v[158:161], v[162:165], v[48:51]
	ds_read_b64_tr_b16 v[174:175], v215 offset:40960
	ds_read_b64_tr_b16 v[176:177], v215 offset:45056
	s_waitcnt lgkmcnt(4)
	v_mfma_f32_16x16x32_bf16 v[52:55], v[158:161], v[166:169], v[52:55]
	v_mfma_f32_16x16x32_bf16 v[20:23], v[150:153], v[166:169], v[20:23]
	s_waitcnt lgkmcnt(2)
	v_mfma_f32_16x16x32_bf16 v[24:27], v[150:153], v[170:173], v[24:27]
	v_mfma_f32_16x16x32_bf16 v[56:59], v[158:161], v[170:173], v[56:59]
	s_waitcnt lgkmcnt(0)
	v_mfma_f32_16x16x32_bf16 v[60:63], v[158:161], v[174:177], v[60:63]
	v_mfma_f32_16x16x32_bf16 v[28:31], v[150:153], v[174:177], v[28:31]
	s_waitcnt vmcnt(5)
	s_barrier
; __device__ __forceinline__ void qkt(f32x16& p0, f32x16& p1, const char* Ks, const bf16x8* qr, const char* qL, int r32, int hi, float negm) {
; #pragma unroll
;   for (int r = 0; r < 16; ++r) { p0[r] = negm; p1[r] = negm; }
; #pragma unroll
;   for (int d0 = 0; d0 < 12; ++d0) { int cb = (d0 * 16 + hi * 8) * 2;
;     bf16x8 b0 = *reinterpret_cast<const bf16x8*>(Ks + KSWZ(r32, cb));
;     bf16x8 b1 = *reinterpret_cast<const bf16x8*>(Ks + KSWZ(32 + r32, cb));
;     const bf16x8 q = d0 < 8 ? qr[d0 < 8 ? d0 : 0] : *reinterpret_cast<const bf16x8*>(qL + (d0 - 8) * 1024);
;     p0 = __builtin_amdgcn_mfma_f32_32x32x16_bf16(b0, q, p0, 0, 0, 0);
;     p1 = __builtin_amdgcn_mfma_f32_32x32x16_bf16(b1, q, p1, 0, 0, 0); }
; }
	s_add_i32 m0, s43, 98304
	s_nop 0
	global_load_lds_dwordx4 v[178:179], off
	s_add_i32 m0, s43, 106496
	s_nop 0
	global_load_lds_dwordx4 v[180:181], off
	s_add_i32 m0, s43, 114688
	s_nop 0
	global_load_lds_dwordx4 v[182:183], off
	s_add_i32 m0, s43, 32768
	s_nop 0
	global_load_lds_dwordx4 v[184:185], off
	s_add_i32 m0, s43, 40960
	s_nop 0
	global_load_lds_dwordx4 v[186:187], off
	v_lshl_add_u64 v[178:179], v[178:179], 0, v[188:189]
	v_lshl_add_u64 v[180:181], v[180:181], 0, v[190:191]
	v_lshl_add_u64 v[182:183], v[182:183], 0, v[192:193]
	v_lshl_add_u64 v[184:185], v[184:185], 0, s[22:23]
	v_lshl_add_u64 v[186:187], v[186:187], 0, s[22:23]
	ds_read_b128 v[162:165], v202 offset:0
	ds_read_b128 v[166:169], v202 offset:6144
	ds_read_b128 v[170:173], v202 offset:12288
	s_waitcnt lgkmcnt(2)
	v_mfma_f32_16x16x32_bf16 v[114:117], v[162:165], v[64:67], v[224:227]
	v_mfma_f32_16x16x32_bf16 v[118:121], v[162:165], v[88:91], v[228:231]
	ds_read_b128 v[174:177], v202 offset:18432
	s_waitcnt lgkmcnt(2)
	v_mfma_f32_16x16x32_bf16 v[126:129], v[166:169], v[88:91], v[228:231]
	v_mfma_f32_16x16x32_bf16 v[122:125], v[166:169], v[64:67], v[224:227]
	ds_read_b128 v[162:165], v203 offset:0
	s_waitcnt lgkmcnt(2)
	v_mfma_f32_16x16x32_bf16 v[130:133], v[170:173], v[64:67], v[224:227]
	v_mfma_f32_16x16x32_bf16 v[134:137], v[170:173], v[88:91], v[228:231]
	ds_read_b128 v[166:169], v203 offset:6144
	s_waitcnt lgkmcnt(2)
	v_mfma_f32_16x16x32_bf16 v[142:145], v[174:177], v[88:91], v[228:231]
	v_mfma_f32_16x16x32_bf16 v[138:141], v[174:177], v[64:67], v[224:227]
	ds_read_b128 v[170:173], v203 offset:12288
	s_waitcnt lgkmcnt(2)
	v_mfma_f32_16x16x32_bf16 v[114:117], v[162:165], v[68:71], v[114:117]
	v_mfma_f32_16x16x32_bf16 v[118:121], v[162:165], v[92:95], v[118:121]
	ds_read_b128 v[174:177], v203 offset:18432
	s_waitcnt lgkmcnt(2)
	v_mfma_f32_16x16x32_bf16 v[126:129], v[166:169], v[92:95], v[126:129]
	v_mfma_f32_16x16x32_bf16 v[122:125], v[166:169], v[68:71], v[122:125]
	ds_read_b128 v[162:165], v202 offset:128
	s_waitcnt lgkmcnt(2)
	v_mfma_f32_16x16x32_bf16 v[130:133], v[170:173], v[68:71], v[130:133]
	v_mfma_f32_16x16x32_bf16 v[134:137], v[170:173], v[92:95], v[134:137]
	ds_read_b128 v[166:169], v202 offset:6272
	s_waitcnt lgkmcnt(2)
	v_mfma_f32_16x16x32_bf16 v[142:145], v[174:177], v[92:95], v[142:145]
	v_mfma_f32_16x16x32_bf16 v[138:141], v[174:177], v[68:71], v[138:141]
	ds_read_b128 v[170:173], v202 offset:12416
	s_waitcnt lgkmcnt(2)
	v_mfma_f32_16x16x32_bf16 v[114:117], v[162:165], v[72:75], v[114:117]
	v_mfma_f32_16x16x32_bf16 v[118:121], v[162:165], v[96:99], v[118:121]
	ds_read_b128 v[174:177], v202 offset:18560
	s_waitcnt lgkmcnt(2)
	v_mfma_f32_16x16x32_bf16 v[126:129], v[166:169], v[96:99], v[126:129]
	v_mfma_f32_16x16x32_bf16 v[122:125], v[166:169], v[72:75], v[122:125]
	ds_read_b128 v[162:165], v203 offset:128
	s_waitcnt lgkmcnt(2)
	v_mfma_f32_16x16x32_bf16 v[130:133], v[170:173], v[72:75], v[130:133]
	v_mfma_f32_16x16x32_bf16 v[134:137], v[170:173], v[96:99], v[134:137]
	ds_read_b128 v[166:169], v203 offset:6272
	s_waitcnt lgkmcnt(2)
	v_mfma_f32_16x16x32_bf16 v[142:145], v[174:177], v[96:99], v[142:145]
	v_mfma_f32_16x16x32_bf16 v[138:141], v[174:177], v[72:75], v[138:141]
	ds_read_b128 v[170:173], v203 offset:12416
	s_waitcnt lgkmcnt(2)
	v_mfma_f32_16x16x32_bf16 v[114:117], v[162:165], v[76:79], v[114:117]
	v_mfma_f32_16x16x32_bf16 v[118:121], v[162:165], v[100:103], v[118:121]
	ds_read_b128 v[174:177], v203 offset:18560
	s_waitcnt lgkmcnt(2)
	v_mfma_f32_16x16x32_bf16 v[126:129], v[166:169], v[100:103], v[126:129]
	v_mfma_f32_16x16x32_bf16 v[122:125], v[166:169], v[76:79], v[122:125]
	ds_read_b128 v[162:165], v202 offset:256
	s_waitcnt lgkmcnt(2)
	v_mfma_f32_16x16x32_bf16 v[130:133], v[170:173], v[76:79], v[130:133]
	v_mfma_f32_16x16x32_bf16 v[134:137], v[170:173], v[100:103], v[134:137]
	ds_read_b128 v[166:169], v202 offset:6400
	s_waitcnt lgkmcnt(2)
	v_mfma_f32_16x16x32_bf16 v[142:145], v[174:177], v[100:103], v[142:145]
	v_mfma_f32_16x16x32_bf16 v[138:141], v[174:177], v[76:79], v[138:141]
	ds_read_b128 v[170:173], v202 offset:12544
	s_waitcnt lgkmcnt(2)
	v_mfma_f32_16x16x32_bf16 v[114:117], v[162:165], v[80:83], v[114:117]
	v_mfma_f32_16x16x32_bf16 v[118:121], v[162:165], v[104:107], v[118:121]
	ds_read_b128 v[174:177], v202 offset:18688
	s_waitcnt lgkmcnt(2)
	v_mfma_f32_16x16x32_bf16 v[126:129], v[166:169], v[104:107], v[126:129]
	v_mfma_f32_16x16x32_bf16 v[122:125], v[166:169], v[80:83], v[122:125]
	ds_read_b128 v[162:165], v203 offset:256
	s_waitcnt lgkmcnt(2)
	v_mfma_f32_16x16x32_bf16 v[130:133], v[170:173], v[80:83], v[130:133]
	v_mfma_f32_16x16x32_bf16 v[134:137], v[170:173], v[104:107], v[134:137]
	ds_read_b128 v[166:169], v203 offset:6400
	s_waitcnt lgkmcnt(2)
	v_mfma_f32_16x16x32_bf16 v[142:145], v[174:177], v[104:107], v[142:145]
	v_mfma_f32_16x16x32_bf16 v[138:141], v[174:177], v[80:83], v[138:141]
	ds_read_b128 v[170:173], v203 offset:12544
	s_waitcnt lgkmcnt(2)
	v_mfma_f32_16x16x32_bf16 v[114:117], v[162:165], v[84:87], v[114:117]
	v_mfma_f32_16x16x32_bf16 v[118:121], v[162:165], v[108:111], v[118:121]
	ds_read_b128 v[174:177], v203 offset:18688
	s_waitcnt lgkmcnt(2)
	v_mfma_f32_16x16x32_bf16 v[126:129], v[166:169], v[108:111], v[126:129]
	v_mfma_f32_16x16x32_bf16 v[122:125], v[166:169], v[84:87], v[122:125]
	s_waitcnt lgkmcnt(1)
	v_mfma_f32_16x16x32_bf16 v[130:133], v[170:173], v[84:87], v[130:133]
	v_mfma_f32_16x16x32_bf16 v[134:137], v[170:173], v[108:111], v[134:137]
	s_waitcnt lgkmcnt(0)
	v_mfma_f32_16x16x32_bf16 v[142:145], v[174:177], v[108:111], v[142:145]
	v_mfma_f32_16x16x32_bf16 v[138:141], v[174:177], v[84:87], v[138:141]
	ds_read_b64_tr_b16 v[162:163], v208 offset:0
	ds_read_b64_tr_b16 v[164:165], v208 offset:4096
	ds_read_b64_tr_b16 v[166:167], v209 offset:0
	ds_read_b64_tr_b16 v[168:169], v209 offset:4096
	ds_read_b64_tr_b16 v[170:171], v210 offset:0
	ds_read_b64_tr_b16 v[172:173], v210 offset:4096
	s_nop 7
	v_max3_f32 v232, v114, v115, v116
	v_max_f32_e32 v232, v232, v117
	v_max3_f32 v233, v118, v119, v120
	v_max_f32_e32 v233, v233, v121
	v_max3_f32 v232, v232, v122, v123
	v_max3_f32 v232, v232, v124, v125
	v_max3_f32 v233, v233, v126, v127
	v_max3_f32 v233, v233, v128, v129
	v_max3_f32 v232, v232, v130, v131
	v_max3_f32 v232, v232, v132, v133
	v_max3_f32 v233, v233, v134, v135
	v_max3_f32 v233, v233, v136, v137
	v_max3_f32 v232, v232, v138, v139
	v_max3_f32 v232, v232, v140, v141
	v_max3_f32 v233, v233, v142, v143
	v_max3_f32 v233, v233, v144, v145
	v_max_f32_e32 v234, v232, v233
	v_cmp_ge_f32_e32 vcc, s38, v234
	s_cmp_eq_u64 vcc, exec
	s_cbranch_scc0 .Lat_rare_3
; __device__ __forceinline__ void finishSM(f32x16& p0, f32x16& p1, float alpha, float& l_reg, bf16x8& pa0, bf16x8& pa1, bf16x8& pa2, bf16x8& pa3) {
; #pragma unroll
;   for (int r = 0; r < 16; ++r) p1[r] = __builtin_amdgcn_exp2f(p1[r]);
;   float ps = 0;
; #pragma unroll
;   for (int r = 0; r < 16; ++r) ps += p0[r];
; #pragma unroll
;   for (int r = 0; r < 16; ++r) ps += p1[r];
;   { auto rr = __builtin_amdgcn_permlane32_swap(__float_as_uint(ps), __float_as_uint(ps), false, false);
;     ps = __uint_as_float(rr[0]) + __uint_as_float(rr[1]); }
;   l_reg = l_reg * alpha + ps;
;     ...
;   PK4(p0, 0, pa0); PK4(p0, 8, pa1); PK4(p1, 0, pa2); PK4(p1, 8, pa3);
;     ...
; }
; __device__ __forceinline__ void qkt(f32x16& p0, f32x16& p1, const char* Ks, const bf16x8* qr, const char* qL, int r32, int hi, float negm) {
; #pragma unroll
;   for (int r = 0; r < 16; ++r) { p0[r] = negm; p1[r] = negm; }
; #pragma unroll
;   for (int d0 = 0; d0 < 12; ++d0) { int cb = (d0 * 16 + hi * 8) * 2;
;     bf16x8 b0 = *reinterpret_cast<const bf16x8*>(Ks + KSWZ(r32, cb));
;     bf16x8 b1 = *reinterpret_cast<const bf16x8*>(Ks + KSWZ(32 + r32, cb));
;     const bf16x8 q = d0 < 8 ? qr[d0 < 8 ? d0 : 0] : *reinterpret_cast<const bf16x8*>(qL + (d0 - 8) * 1024);
;     p0 = __builtin_amdgcn_mfma_f32_32x32x16_bf16(b0, q, p0, 0, 0, 0);
;     p1 = __builtin_amdgcn_mfma_f32_32x32x16_bf16(b1, q, p1, 0, 0, 0); }
; }
; __device__ __forceinline__ int v_st(int k, int c) { const int kk = (k & ~0xC) | ((k & 4) << 1) | ((k & 8) >> 1); return ((kk >> 3) * 4 + (c >> 5)) * 512 + ((kk & 7) * 32 + (c & 31)) * 2; }
; __device__ __forceinline__ int v_rd_base(int lane) { return ((lane & 3) << 3) | (((lane >> 2) & 3) << 6) | (((lane >> 4) & 1) << 5) | (((lane >> 5) & 1) << 8); }
; template <int OFF> __device__ __forceinline__ s16x4 tr_read(int vb) {
;   s16x4 r; asm volatile("ds_read_b64_tr_b16 %0, %1 offset:%2" : "=&v"(r) : "v"(vb), "i"(OFF) : "memory"); return r;
; }
; template <int D0> __device__ __forceinline__ void pv_one(f32x16& od, int vb, bf16x8 pa0, bf16x8 pa1, bf16x8 pa2, bf16x8 pa3) {
;   const s16x4 l0 = tr_read<v_rd_off(D0, 0, 0)>(vb), h0 = tr_read<v_rd_off(D0, 0, 1)>(vb), l1 = tr_read<v_rd_off(D0, 1, 0)>(vb), h1 = tr_read<v_rd_off(D0, 1, 1)>(vb);
;   const s16x4 l2 = tr_read<v_rd_off(D0, 2, 0)>(vb), h2 = tr_read<v_rd_off(D0, 2, 1)>(vb), l3 = tr_read<v_rd_off(D0, 3, 0)>(vb), h3 = tr_read<v_rd_off(D0, 3, 1)>(vb);
.Lat_cont_3:
	v_exp_f32_e32 v114, v114
	v_exp_f32_e32 v115, v115
	v_exp_f32_e32 v116, v116
	v_exp_f32_e32 v117, v117
	v_add_f32_e32 v220, v220, v114
	v_add_f32_e32 v220, v220, v115
	v_add_f32_e32 v220, v220, v116
	v_add_f32_e32 v220, v220, v117
	v_exp_f32_e32 v122, v122
	v_exp_f32_e32 v123, v123
	v_exp_f32_e32 v124, v124
	v_exp_f32_e32 v125, v125
	v_add_f32_e32 v220, v220, v122
	v_add_f32_e32 v220, v220, v123
	v_add_f32_e32 v220, v220, v124
	v_add_f32_e32 v220, v220, v125
	v_cvt_pk_bf16_f32 v146, v114, v115
	v_cvt_pk_bf16_f32 v147, v116, v117
	v_cvt_pk_bf16_f32 v148, v122, v123
	v_cvt_pk_bf16_f32 v149, v124, v125
	v_exp_f32_e32 v118, v118
	v_exp_f32_e32 v119, v119
	v_exp_f32_e32 v120, v120
	v_exp_f32_e32 v121, v121
	v_add_f32_e32 v221, v221, v118
	v_add_f32_e32 v221, v221, v119
	v_add_f32_e32 v221, v221, v120
	v_add_f32_e32 v221, v221, v121
	v_exp_f32_e32 v126, v126
	v_exp_f32_e32 v127, v127
	v_exp_f32_e32 v128, v128
	v_exp_f32_e32 v129, v129
	v_add_f32_e32 v221, v221, v126
	v_add_f32_e32 v221, v221, v127
	v_add_f32_e32 v221, v221, v128
	v_add_f32_e32 v221, v221, v129
	v_cvt_pk_bf16_f32 v154, v118, v119
	v_cvt_pk_bf16_f32 v155, v120, v121
	v_cvt_pk_bf16_f32 v156, v126, v127
	v_cvt_pk_bf16_f32 v157, v128, v129
	s_nop 1
	s_waitcnt lgkmcnt(4)
	v_mfma_f32_16x16x32_bf16 v[0:3], v[146:149], v[162:165], v[0:3]
	v_mfma_f32_16x16x32_bf16 v[32:35], v[154:157], v[162:165], v[32:35]
	ds_read_b64_tr_b16 v[174:175], v211 offset:0
	ds_read_b64_tr_b16 v[176:177], v211 offset:4096
	v_exp_f32_e32 v130, v130
	v_exp_f32_e32 v131, v131
	v_exp_f32_e32 v132, v132
	v_exp_f32_e32 v133, v133
	v_add_f32_e32 v220, v220, v130
	s_waitcnt lgkmcnt(4)
	v_mfma_f32_16x16x32_bf16 v[36:39], v[154:157], v[166:169], v[36:39]
	v_mfma_f32_16x16x32_bf16 v[4:7], v[146:149], v[166:169], v[4:7]
	ds_read_b64_tr_b16 v[162:163], v212 offset:0
	ds_read_b64_tr_b16 v[164:165], v212 offset:4096
	v_add_f32_e32 v220, v220, v131
	v_add_f32_e32 v220, v220, v132
	v_add_f32_e32 v220, v220, v133
	v_exp_f32_e32 v138, v138
	v_exp_f32_e32 v139, v139
	s_waitcnt lgkmcnt(4)
	v_mfma_f32_16x16x32_bf16 v[8:11], v[146:149], v[170:173], v[8:11]
	v_mfma_f32_16x16x32_bf16 v[40:43], v[154:157], v[170:173], v[40:43]
	ds_read_b64_tr_b16 v[166:167], v213 offset:0
	ds_read_b64_tr_b16 v[168:169], v213 offset:4096
	v_exp_f32_e32 v140, v140
	v_exp_f32_e32 v141, v141
	v_add_f32_e32 v220, v220, v138
	v_add_f32_e32 v220, v220, v139
	v_add_f32_e32 v220, v220, v140
	s_waitcnt lgkmcnt(4)
	v_mfma_f32_16x16x32_bf16 v[44:47], v[154:157], v[174:177], v[44:47]
	v_mfma_f32_16x16x32_bf16 v[12:15], v[146:149], v[174:177], v[12:15]
	ds_read_b64_tr_b16 v[170:171], v214 offset:0
	ds_read_b64_tr_b16 v[172:173], v214 offset:4096
	v_add_f32_e32 v220, v220, v141
	v_cvt_pk_bf16_f32 v150, v130, v131
	v_cvt_pk_bf16_f32 v151, v132, v133
	v_cvt_pk_bf16_f32 v152, v138, v139
	v_cvt_pk_bf16_f32 v153, v140, v141
	s_waitcnt lgkmcnt(4)
	v_mfma_f32_16x16x32_bf16 v[16:19], v[146:149], v[162:165], v[16:19]
	v_mfma_f32_16x16x32_bf16 v[48:51], v[154:157], v[162:165], v[48:51]
	ds_read_b64_tr_b16 v[174:175], v215 offset:0
	ds_read_b64_tr_b16 v[176:177], v215 offset:4096
	v_exp_f32_e32 v134, v134
	v_exp_f32_e32 v135, v135
	v_exp_f32_e32 v136, v136
	v_exp_f32_e32 v137, v137
	v_add_f32_e32 v221, v221, v134
	s_waitcnt lgkmcnt(4)
	v_mfma_f32_16x16x32_bf16 v[52:55], v[154:157], v[166:169], v[52:55]
	v_mfma_f32_16x16x32_bf16 v[20:23], v[146:149], v[166:169], v[20:23]
	ds_read_b64_tr_b16 v[162:163], v208 offset:8192
	ds_read_b64_tr_b16 v[164:165], v208 offset:12288
	v_add_f32_e32 v221, v221, v135
	v_add_f32_e32 v221, v221, v136
	v_add_f32_e32 v221, v221, v137
	v_exp_f32_e32 v142, v142
	v_exp_f32_e32 v143, v143
	s_waitcnt lgkmcnt(4)
	v_mfma_f32_16x16x32_bf16 v[24:27], v[146:149], v[170:173], v[24:27]
	v_mfma_f32_16x16x32_bf16 v[56:59], v[154:157], v[170:173], v[56:59]
	ds_read_b64_tr_b16 v[166:167], v209 offset:8192
	ds_read_b64_tr_b16 v[168:169], v209 offset:12288
	v_exp_f32_e32 v144, v144
	v_exp_f32_e32 v145, v145
	v_add_f32_e32 v221, v221, v142
	v_add_f32_e32 v221, v221, v143
	v_add_f32_e32 v221, v221, v144
	s_waitcnt lgkmcnt(4)
	v_mfma_f32_16x16x32_bf16 v[60:63], v[154:157], v[174:177], v[60:63]
	v_mfma_f32_16x16x32_bf16 v[28:31], v[146:149], v[174:177], v[28:31]
	ds_read_b64_tr_b16 v[170:171], v210 offset:8192
	ds_read_b64_tr_b16 v[172:173], v210 offset:12288
	v_add_f32_e32 v221, v221, v145
	v_cvt_pk_bf16_f32 v158, v134, v135
	v_cvt_pk_bf16_f32 v159, v136, v137
	v_cvt_pk_bf16_f32 v160, v142, v143
	v_cvt_pk_bf16_f32 v161, v144, v145
	s_waitcnt lgkmcnt(4)
	s_nop 1
	v_mfma_f32_16x16x32_bf16 v[0:3], v[150:153], v[162:165], v[0:3]
	v_mfma_f32_16x16x32_bf16 v[32:35], v[158:161], v[162:165], v[32:35]
	ds_read_b64_tr_b16 v[174:175], v211 offset:8192
	ds_read_b64_tr_b16 v[176:177], v211 offset:12288
	s_waitcnt lgkmcnt(4)
	v_mfma_f32_16x16x32_bf16 v[36:39], v[158:161], v[166:169], v[36:39]
	v_mfma_f32_16x16x32_bf16 v[4:7], v[150:153], v[166:169], v[4:7]
	ds_read_b64_tr_b16 v[162:163], v212 offset:8192
	ds_read_b64_tr_b16 v[164:165], v212 offset:12288
	s_waitcnt lgkmcnt(4)
	v_mfma_f32_16x16x32_bf16 v[8:11], v[150:153], v[170:173], v[8:11]
	v_mfma_f32_16x16x32_bf16 v[40:43], v[158:161], v[170:173], v[40:43]
	ds_read_b64_tr_b16 v[166:167], v213 offset:8192
	ds_read_b64_tr_b16 v[168:169], v213 offset:12288
	s_waitcnt lgkmcnt(4)
	v_mfma_f32_16x16x32_bf16 v[44:47], v[158:161], v[174:177], v[44:47]
	v_mfma_f32_16x16x32_bf16 v[12:15], v[150:153], v[174:177], v[12:15]
	ds_read_b64_tr_b16 v[170:171], v214 offset:8192
	ds_read_b64_tr_b16 v[172:173], v214 offset:12288
	s_waitcnt lgkmcnt(4)
	v_mfma_f32_16x16x32_bf16 v[16:19], v[150:153], v[162:165], v[16:19]
	v_mfma_f32_16x16x32_bf16 v[48:51], v[158:161], v[162:165], v[48:51]
	ds_read_b64_tr_b16 v[174:175], v215 offset:8192
	ds_read_b64_tr_b16 v[176:177], v215 offset:12288
	s_waitcnt lgkmcnt(4)
	v_mfma_f32_16x16x32_bf16 v[52:55], v[158:161], v[166:169], v[52:55]
	v_mfma_f32_16x16x32_bf16 v[20:23], v[150:153], v[166:169], v[20:23]
	s_waitcnt lgkmcnt(2)
	v_mfma_f32_16x16x32_bf16 v[24:27], v[150:153], v[170:173], v[24:27]
	v_mfma_f32_16x16x32_bf16 v[56:59], v[158:161], v[170:173], v[56:59]
	s_waitcnt lgkmcnt(0)
	v_mfma_f32_16x16x32_bf16 v[60:63], v[158:161], v[174:177], v[60:63]
	v_mfma_f32_16x16x32_bf16 v[28:31], v[150:153], v[174:177], v[28:31]
	s_waitcnt vmcnt(5)
	s_barrier
; __device__ __forceinline__ unsigned f2bf(float f) { unsigned u = __float_as_uint(f); return (u + 0x7fffu + ((u >> 16) & 1u)) >> 16; }
; #define SBAR() __builtin_amdgcn_sched_barrier(0)
; __device__ __forceinline__ int crow(int r, int hi) { return (r & 3) + 8 * (r >> 2) + 4 * hi; }
; #define SWRITE(b, i) do { *(bf16x8*)(V_lds + (b) * SHM_V + vst0) = sr_[i].vs0; *(bf16x8*)(V_lds + (b) * SHM_V + vst1) = sr_[i].vs1; \
;     *(bf16x8*)(K_lds + (b) * SHM_K + kst0) = sr_[i].ks0; *(bf16x8*)(K_lds + (b) * SHM_K + kst1) = sr_[i].ks1; *(bf16x8*)(K_lds + (b) * SHM_K + kst2) = sr_[i].ks2; } while (0)
; #define SWAIT() do { if constexpr (SDEPTH == 2) asm volatile("s_waitcnt vmcnt(5)" ::: "memory"); else asm volatile("s_waitcnt vmcnt(0)" ::: "memory"); } while (0)
; #define RESC(a) do { if (__any((a) < 1.f)) { if (hi == 0) al_l[r32] = (a); asm volatile("s_waitcnt lgkmcnt(0)" ::: "memory"); \
;     _Pragma("unroll") for (int d = 0; d < 4; ++d) _Pragma("unroll") for (int r = 0; r < 16; ++r) o[d][r] *= al_l[crow(r, hi)]; } } while (0)
; __device__ __forceinline__ void attn_unit(const bf16_t* __restrict__ Qb, const bf16_t* __restrict__ Kn, const bf16_t* __restrict__ Kr, const bf16_t* __restrict__ Vh,
;                                           bf16_t* __restrict__ Ob, char* lds) {
;     ...
;     __syncthreads(); SWAIT(); SWRITE(1, SO);
;     RESC(alA); __syncthreads();
;   }
;   SBAR(); qkt(pB0, pB1, K_lds + SHM_K, qr, qL, r32, hi, -m_reg);
;   finishSM(pA0, pA1, alA, l_reg, pa0, pa1, pa2, pa3); SBAR();
;   pv_d0(o, vb0, pa0, pa1, pa2, pa3); partialSM<false>(pB0, pB1, m_reg, alB);
;   __syncthreads(); RESC(alB);
;   finishSM(pB0, pB1, alB, l_reg, pa0, pa1, pa2, pa3); SBAR();
;   pv_d0(o, vb0 + (int)SHM_V, pa0, pa1, pa2, pa3);
;   if (hi == 0) li_l[r32] = l_reg; asm volatile("s_waitcnt lgkmcnt(0)" ::: "memory");
;   float rli[16];
; #pragma unroll
;   for (int r = 0; r < 16; ++r) rli[r] = __builtin_amdgcn_rcpf(li_l[crow(r, hi)]);
;   bf16_t* Ow = Ob + (long)(wid * 32) * DM;
; #pragma unroll
;   for (int r = 0; r < 16; ++r) { int orow = crow(r, hi);
; #pragma unroll
;     for (int d0 = 0; d0 < 4; ++d0) Ow[(long)orow * DM + d0 * 32 + r32] = (bf16_t)f2bf(o[d0][r] * rli[r]); }
	s_sub_u32 s39, s39, 1
	s_cmp_lg_u32 s39, 0
	s_cbranch_scc1 .Lat_loop
	v_mov_b32_e32 v235, v220
	s_nop 1
	v_permlane32_swap_b32_e32 v220, v235
	s_nop 1
	v_add_f32_e32 v220, v220, v235
	s_nop 1
	ds_bpermute_b32 v235, v112, v220
	s_waitcnt lgkmcnt(0)
	v_add_f32_e32 v220, v220, v235
	v_rcp_f32_e32 v220, v220
	s_nop 0
	ds_write_b32 v216, v220 offset:0
	v_mov_b32_e32 v235, v221
	s_nop 1
	v_permlane32_swap_b32_e32 v221, v235
	s_nop 1
	v_add_f32_e32 v221, v221, v235
	s_nop 1
	ds_bpermute_b32 v235, v112, v221
	s_waitcnt lgkmcnt(0)
	v_add_f32_e32 v221, v221, v235
	v_rcp_f32_e32 v221, v221
	s_nop 0
	ds_write_b32 v216, v221 offset:64
	s_waitcnt lgkmcnt(0)
	v_and_b32_e32 v234, 63, v195
	v_lshrrev_b32_e32 v235, 4, v234
	v_and_b32_e32 v234, 15, v234
	v_lshlrev_b32_e32 v234, 1, v234
	v_lshl_add_u32 v234, v235, 14, v234
	ds_read_b128 v[246:249], v217 offset:0
	s_waitcnt lgkmcnt(0)
	s_add_u32 s74, s36, 0
	s_addc_u32 s75, s37, 0
	v_mul_f32_e32 v0, v0, v246
	v_mul_f32_e32 v4, v4, v246
	v_cvt_pk_bf16_f32 v0, v0, v4
	s_nop 0
	global_store_short v234, v0, s[74:75] offset:0
	global_store_short_d16_hi v234, v0, s[74:75] offset:32
	v_mul_f32_e32 v8, v8, v246
	v_mul_f32_e32 v12, v12, v246
	v_cvt_pk_bf16_f32 v8, v8, v12
	s_nop 0
	global_store_short v234, v8, s[74:75] offset:64
	global_store_short_d16_hi v234, v8, s[74:75] offset:96
	v_mul_f32_e32 v16, v16, v246
	v_mul_f32_e32 v20, v20, v246
	v_cvt_pk_bf16_f32 v16, v16, v20
	s_nop 0
	global_store_short v234, v16, s[74:75] offset:128
	global_store_short_d16_hi v234, v16, s[74:75] offset:160
	v_mul_f32_e32 v24, v24, v246
	v_mul_f32_e32 v28, v28, v246
	v_cvt_pk_bf16_f32 v24, v24, v28
	s_nop 0
	global_store_short v234, v24, s[74:75] offset:192
	global_store_short_d16_hi v234, v24, s[74:75] offset:224
	s_add_u32 s74, s36, 4096
	s_addc_u32 s75, s37, 0
	v_mul_f32_e32 v1, v1, v247
	v_mul_f32_e32 v5, v5, v247
	v_cvt_pk_bf16_f32 v1, v1, v5
	s_nop 0
	global_store_short v234, v1, s[74:75] offset:0
	global_store_short_d16_hi v234, v1, s[74:75] offset:32
	v_mul_f32_e32 v9, v9, v247
	v_mul_f32_e32 v13, v13, v247
	v_cvt_pk_bf16_f32 v9, v9, v13
	s_nop 0
	global_store_short v234, v9, s[74:75] offset:64
	global_store_short_d16_hi v234, v9, s[74:75] offset:96
	v_mul_f32_e32 v17, v17, v247
	v_mul_f32_e32 v21, v21, v247
	v_cvt_pk_bf16_f32 v17, v17, v21
	s_nop 0
	global_store_short v234, v17, s[74:75] offset:128
	global_store_short_d16_hi v234, v17, s[74:75] offset:160
	v_mul_f32_e32 v25, v25, v247
	v_mul_f32_e32 v29, v29, v247
	v_cvt_pk_bf16_f32 v25, v25, v29
	s_nop 0
	global_store_short v234, v25, s[74:75] offset:192
	global_store_short_d16_hi v234, v25, s[74:75] offset:224
	s_add_u32 s74, s36, 8192
	s_addc_u32 s75, s37, 0
	v_mul_f32_e32 v2, v2, v248
	v_mul_f32_e32 v6, v6, v248
	v_cvt_pk_bf16_f32 v2, v2, v6
	s_nop 0
	global_store_short v234, v2, s[74:75] offset:0
	global_store_short_d16_hi v234, v2, s[74:75] offset:32
	v_mul_f32_e32 v10, v10, v248
	v_mul_f32_e32 v14, v14, v248
	v_cvt_pk_bf16_f32 v10, v10, v14
	s_nop 0
	global_store_short v234, v10, s[74:75] offset:64
	global_store_short_d16_hi v234, v10, s[74:75] offset:96
	v_mul_f32_e32 v18, v18, v248
	v_mul_f32_e32 v22, v22, v248
	v_cvt_pk_bf16_f32 v18, v18, v22
	s_nop 0
	global_store_short v234, v18, s[74:75] offset:128
	global_store_short_d16_hi v234, v18, s[74:75] offset:160
	v_mul_f32_e32 v26, v26, v248
	v_mul_f32_e32 v30, v30, v248
	v_cvt_pk_bf16_f32 v26, v26, v30
	s_nop 0
	global_store_short v234, v26, s[74:75] offset:192
	global_store_short_d16_hi v234, v26, s[74:75] offset:224
	s_add_u32 s74, s36, 12288
	s_addc_u32 s75, s37, 0
	v_mul_f32_e32 v3, v3, v249
	v_mul_f32_e32 v7, v7, v249
	v_cvt_pk_bf16_f32 v3, v3, v7
	s_nop 0
	global_store_short v234, v3, s[74:75] offset:0
	global_store_short_d16_hi v234, v3, s[74:75] offset:32
	v_mul_f32_e32 v11, v11, v249
	v_mul_f32_e32 v15, v15, v249
	v_cvt_pk_bf16_f32 v11, v11, v15
	s_nop 0
	global_store_short v234, v11, s[74:75] offset:64
	global_store_short_d16_hi v234, v11, s[74:75] offset:96
	v_mul_f32_e32 v19, v19, v249
	v_mul_f32_e32 v23, v23, v249
	v_cvt_pk_bf16_f32 v19, v19, v23
	s_nop 0
	global_store_short v234, v19, s[74:75] offset:128
	global_store_short_d16_hi v234, v19, s[74:75] offset:160
	v_mul_f32_e32 v27, v27, v249
	v_mul_f32_e32 v31, v31, v249
	v_cvt_pk_bf16_f32 v27, v27, v31
	s_nop 0
	global_store_short v234, v27, s[74:75] offset:192
	global_store_short_d16_hi v234, v27, s[74:75] offset:224
	ds_read_b128 v[246:249], v217 offset:64
	s_waitcnt lgkmcnt(0)
; __device__ __forceinline__ unsigned f2bf(float f) { unsigned u = __float_as_uint(f); return (u + 0x7fffu + ((u >> 16) & 1u)) >> 16; }
; __device__ __forceinline__ int crow(int r, int hi) { return (r & 3) + 8 * (r >> 2) + 4 * hi; }
; template <bool FIRST>
; __device__ __forceinline__ void partialSM(f32x16& p0, f32x16& p1, float& m_reg, float& alpha) {
;   constexpr float THR2 = THR * 1.4426950408889634f;
;   float pmax = p0[0];
; #pragma unroll
;   for (int r = 1; r < 16; ++r) pmax = fmaxf(pmax, p0[r]);
; #pragma unroll
;   for (int r = 0; r < 16; ++r) pmax = fmaxf(pmax, p1[r]);
;   { auto rr = __builtin_amdgcn_permlane32_swap(__float_as_uint(pmax), __float_as_uint(pmax), false, false);
;     pmax = fmaxf(__uint_as_float(rr[0]), __uint_as_float(rr[1])); }
;   if (!FIRST && __builtin_expect(__all(pmax <= THR2), 1)) { alpha = 1.f; }
;   else { const float d = FIRST ? pmax : fmaxf(pmax, 0.f); alpha = FIRST ? 1.f : __builtin_amdgcn_exp2f(-d); m_reg += d;
; #pragma unroll
;     for (int r = 0; r < 16; ++r) p0[r] -= d;
; #pragma unroll
;     for (int r = 0; r < 16; ++r) p1[r] -= d; }
; #pragma unroll
;   for (int r = 0; r < 16; ++r) p0[r] = __builtin_amdgcn_exp2f(p0[r]);
; }
; __device__ __forceinline__ void attn_unit(const bf16_t* __restrict__ Qb, const bf16_t* __restrict__ Kn, const bf16_t* __restrict__ Kr, const bf16_t* __restrict__ Vh,
;                                           bf16_t* __restrict__ Ob, char* lds) {
;     ...
;   bf16_t* Ow = Ob + (long)(wid * 32) * DM;
; #pragma unroll
;   for (int r = 0; r < 16; ++r) { int orow = crow(r, hi);
; #pragma unroll
;     for (int d0 = 0; d0 < 4; ++d0) Ow[(long)orow * DM + d0 * 32 + r32] = (bf16_t)f2bf(o[d0][r] * rli[r]); }
	s_add_u32 s74, s36, 65536
	s_addc_u32 s75, s37, 0
	v_mul_f32_e32 v32, v32, v246
	v_mul_f32_e32 v36, v36, v246
	v_cvt_pk_bf16_f32 v32, v32, v36
	s_nop 0
	global_store_short v234, v32, s[74:75] offset:0
	global_store_short_d16_hi v234, v32, s[74:75] offset:32
	v_mul_f32_e32 v40, v40, v246
	v_mul_f32_e32 v44, v44, v246
	v_cvt_pk_bf16_f32 v40, v40, v44
	s_nop 0
	global_store_short v234, v40, s[74:75] offset:64
	global_store_short_d16_hi v234, v40, s[74:75] offset:96
	v_mul_f32_e32 v48, v48, v246
	v_mul_f32_e32 v52, v52, v246
	v_cvt_pk_bf16_f32 v48, v48, v52
	s_nop 0
	global_store_short v234, v48, s[74:75] offset:128
	global_store_short_d16_hi v234, v48, s[74:75] offset:160
	v_mul_f32_e32 v56, v56, v246
	v_mul_f32_e32 v60, v60, v246
	v_cvt_pk_bf16_f32 v56, v56, v60
	s_nop 0
	global_store_short v234, v56, s[74:75] offset:192
	global_store_short_d16_hi v234, v56, s[74:75] offset:224
	s_add_u32 s74, s36, 69632
	s_addc_u32 s75, s37, 0
	v_mul_f32_e32 v33, v33, v247
	v_mul_f32_e32 v37, v37, v247
	v_cvt_pk_bf16_f32 v33, v33, v37
	s_nop 0
	global_store_short v234, v33, s[74:75] offset:0
	global_store_short_d16_hi v234, v33, s[74:75] offset:32
	v_mul_f32_e32 v41, v41, v247
	v_mul_f32_e32 v45, v45, v247
	v_cvt_pk_bf16_f32 v41, v41, v45
	s_nop 0
	global_store_short v234, v41, s[74:75] offset:64
	global_store_short_d16_hi v234, v41, s[74:75] offset:96
	v_mul_f32_e32 v49, v49, v247
	v_mul_f32_e32 v53, v53, v247
	v_cvt_pk_bf16_f32 v49, v49, v53
	s_nop 0
	global_store_short v234, v49, s[74:75] offset:128
	global_store_short_d16_hi v234, v49, s[74:75] offset:160
	v_mul_f32_e32 v57, v57, v247
	v_mul_f32_e32 v61, v61, v247
	v_cvt_pk_bf16_f32 v57, v57, v61
	s_nop 0
	global_store_short v234, v57, s[74:75] offset:192
	global_store_short_d16_hi v234, v57, s[74:75] offset:224
	s_add_u32 s74, s36, 73728
	s_addc_u32 s75, s37, 0
	v_mul_f32_e32 v34, v34, v248
	v_mul_f32_e32 v38, v38, v248
	v_cvt_pk_bf16_f32 v34, v34, v38
	s_nop 0
	global_store_short v234, v34, s[74:75] offset:0
	global_store_short_d16_hi v234, v34, s[74:75] offset:32
	v_mul_f32_e32 v42, v42, v248
	v_mul_f32_e32 v46, v46, v248
	v_cvt_pk_bf16_f32 v42, v42, v46
	s_nop 0
	global_store_short v234, v42, s[74:75] offset:64
	global_store_short_d16_hi v234, v42, s[74:75] offset:96
	v_mul_f32_e32 v50, v50, v248
	v_mul_f32_e32 v54, v54, v248
	v_cvt_pk_bf16_f32 v50, v50, v54
	s_nop 0
	global_store_short v234, v50, s[74:75] offset:128
	global_store_short_d16_hi v234, v50, s[74:75] offset:160
	v_mul_f32_e32 v58, v58, v248
	v_mul_f32_e32 v62, v62, v248
	v_cvt_pk_bf16_f32 v58, v58, v62
	s_nop 0
	global_store_short v234, v58, s[74:75] offset:192
	global_store_short_d16_hi v234, v58, s[74:75] offset:224
	s_add_u32 s74, s36, 77824
	s_addc_u32 s75, s37, 0
	v_mul_f32_e32 v35, v35, v249
	v_mul_f32_e32 v39, v39, v249
	v_cvt_pk_bf16_f32 v35, v35, v39
	s_nop 0
	global_store_short v234, v35, s[74:75] offset:0
	global_store_short_d16_hi v234, v35, s[74:75] offset:32
	v_mul_f32_e32 v43, v43, v249
	v_mul_f32_e32 v47, v47, v249
	v_cvt_pk_bf16_f32 v43, v43, v47
	s_nop 0
	global_store_short v234, v43, s[74:75] offset:64
	global_store_short_d16_hi v234, v43, s[74:75] offset:96
	v_mul_f32_e32 v51, v51, v249
	v_mul_f32_e32 v55, v55, v249
	v_cvt_pk_bf16_f32 v51, v51, v55
	s_nop 0
	global_store_short v234, v51, s[74:75] offset:128
	global_store_short_d16_hi v234, v51, s[74:75] offset:160
	v_mul_f32_e32 v59, v59, v249
	v_mul_f32_e32 v63, v63, v249
	v_cvt_pk_bf16_f32 v59, v59, v63
	s_nop 0
	global_store_short v234, v59, s[74:75] offset:192
	global_store_short_d16_hi v234, v59, s[74:75] offset:224
	s_waitcnt vmcnt(0)
	v_readlane_b32 s6, v254, 15
	s_add_i32 s16, s16, s6
	s_cmp_gt_i32 s16, 63
	s_waitcnt lgkmcnt(0)
	s_barrier
	s_cbranch_scc1 .LBB0_462
	s_branch .LBB0_466
.Lat_rare_0:
	v_mov_b32_e32 v235, v232
	s_nop 1
	v_permlane32_swap_b32_e32 v232, v235
	s_nop 1
	v_max_f32_e32 v232, v232, v235
	s_nop 1
	ds_bpermute_b32 v235, v112, v232
	s_waitcnt lgkmcnt(0)
	v_max_f32_e32 v232, v232, v235
	v_add_f32_e32 v218, v218, v232
	v_exp_f32_e64 v243, -v232
	v_sub_f32_e32 v114, v114, v232
	v_sub_f32_e32 v115, v115, v232
	v_sub_f32_e32 v116, v116, v232
	v_sub_f32_e32 v117, v117, v232
	v_sub_f32_e32 v122, v122, v232
	v_sub_f32_e32 v123, v123, v232
	v_sub_f32_e32 v124, v124, v232
	v_sub_f32_e32 v125, v125, v232
	v_sub_f32_e32 v130, v130, v232
	v_sub_f32_e32 v131, v131, v232
	v_sub_f32_e32 v132, v132, v232
	v_sub_f32_e32 v133, v133, v232
	v_sub_f32_e32 v138, v138, v232
	v_sub_f32_e32 v139, v139, v232
	v_sub_f32_e32 v140, v140, v232
	v_sub_f32_e32 v141, v141, v232
	v_sub_f32_e32 v224, 0, v218
	v_sub_f32_e32 v225, 0, v218
	v_sub_f32_e32 v226, 0, v218
	v_sub_f32_e32 v227, 0, v218
	v_mov_b32_e32 v235, v233
	s_nop 1
	v_permlane32_swap_b32_e32 v233, v235
	s_nop 1
	v_max_f32_e32 v233, v233, v235
	s_nop 1
	ds_bpermute_b32 v235, v112, v233
	s_waitcnt lgkmcnt(0)
	v_max_f32_e32 v233, v233, v235
	v_add_f32_e32 v219, v219, v233
	v_exp_f32_e64 v243, -v233
	v_sub_f32_e32 v118, v118, v233
	v_sub_f32_e32 v119, v119, v233
	v_sub_f32_e32 v120, v120, v233
	v_sub_f32_e32 v121, v121, v233
	v_sub_f32_e32 v126, v126, v233
	v_sub_f32_e32 v127, v127, v233
	v_sub_f32_e32 v128, v128, v233
	v_sub_f32_e32 v129, v129, v233
	v_sub_f32_e32 v134, v134, v233
	v_sub_f32_e32 v135, v135, v233
	v_sub_f32_e32 v136, v136, v233
	v_sub_f32_e32 v137, v137, v233
	v_sub_f32_e32 v142, v142, v233
	v_sub_f32_e32 v143, v143, v233
	v_sub_f32_e32 v144, v144, v233
	v_sub_f32_e32 v145, v145, v233
	v_sub_f32_e32 v228, 0, v219
	v_sub_f32_e32 v229, 0, v219
	v_sub_f32_e32 v230, 0, v219
	v_sub_f32_e32 v231, 0, v219
	s_nop 1
	s_branch .Lat_cont_0
; template <bool FIRST>
; __device__ __forceinline__ void partialSM(f32x16& p0, f32x16& p1, float& m_reg, float& alpha) {
;   constexpr float THR2 = THR * 1.4426950408889634f;
;   float pmax = p0[0];
; #pragma unroll
;   for (int r = 1; r < 16; ++r) pmax = fmaxf(pmax, p0[r]);
; #pragma unroll
;   for (int r = 0; r < 16; ++r) pmax = fmaxf(pmax, p1[r]);
;   { auto rr = __builtin_amdgcn_permlane32_swap(__float_as_uint(pmax), __float_as_uint(pmax), false, false);
;     pmax = fmaxf(__uint_as_float(rr[0]), __uint_as_float(rr[1])); }
;   if (!FIRST && __builtin_expect(__all(pmax <= THR2), 1)) { alpha = 1.f; }
;   else { const float d = FIRST ? pmax : fmaxf(pmax, 0.f); alpha = FIRST ? 1.f : __builtin_amdgcn_exp2f(-d); m_reg += d;
; #pragma unroll
;     for (int r = 0; r < 16; ++r) p0[r] -= d;
; #pragma unroll
;     for (int r = 0; r < 16; ++r) p1[r] -= d; }
; #pragma unroll
;   for (int r = 0; r < 16; ++r) p0[r] = __builtin_amdgcn_exp2f(p0[r]);
; }
.Lat_rare_1:
	v_mov_b32_e32 v235, v232
	s_nop 1
	v_permlane32_swap_b32_e32 v232, v235
	s_nop 1
	v_max_f32_e32 v232, v232, v235
	s_nop 1
	ds_bpermute_b32 v235, v112, v232
	s_waitcnt lgkmcnt(0)
	v_max_f32_e32 v232, v232, v235
	v_max_f32_e32 v232, 0, v232
	v_add_f32_e32 v218, v218, v232
	v_exp_f32_e64 v243, -v232
	v_sub_f32_e32 v114, v114, v232
	v_sub_f32_e32 v115, v115, v232
	v_sub_f32_e32 v116, v116, v232
	v_sub_f32_e32 v117, v117, v232
	v_sub_f32_e32 v122, v122, v232
	v_sub_f32_e32 v123, v123, v232
	v_sub_f32_e32 v124, v124, v232
	v_sub_f32_e32 v125, v125, v232
	v_sub_f32_e32 v130, v130, v232
	v_sub_f32_e32 v131, v131, v232
	v_sub_f32_e32 v132, v132, v232
	v_sub_f32_e32 v133, v133, v232
	v_sub_f32_e32 v138, v138, v232
	v_sub_f32_e32 v139, v139, v232
	v_sub_f32_e32 v140, v140, v232
	v_sub_f32_e32 v141, v141, v232
	v_sub_f32_e32 v224, 0, v218
	v_sub_f32_e32 v225, 0, v218
	v_sub_f32_e32 v226, 0, v218
	v_sub_f32_e32 v227, 0, v218
	v_mul_f32_e32 v220, v220, v243
	ds_write_b32 v216, v243 offset:0
	s_waitcnt lgkmcnt(0)
	ds_read_b128 v[246:249], v217 offset:0
	s_waitcnt lgkmcnt(0)
	v_mul_f32_e32 v0, v0, v246
	v_mul_f32_e32 v1, v1, v247
	v_mul_f32_e32 v2, v2, v248
	v_mul_f32_e32 v3, v3, v249
	v_mul_f32_e32 v4, v4, v246
	v_mul_f32_e32 v5, v5, v247
	v_mul_f32_e32 v6, v6, v248
	v_mul_f32_e32 v7, v7, v249
	v_mul_f32_e32 v8, v8, v246
	v_mul_f32_e32 v9, v9, v247
	v_mul_f32_e32 v10, v10, v248
	v_mul_f32_e32 v11, v11, v249
	v_mul_f32_e32 v12, v12, v246
	v_mul_f32_e32 v13, v13, v247
	v_mul_f32_e32 v14, v14, v248
	v_mul_f32_e32 v15, v15, v249
	v_mul_f32_e32 v16, v16, v246
	v_mul_f32_e32 v17, v17, v247
	v_mul_f32_e32 v18, v18, v248
	v_mul_f32_e32 v19, v19, v249
	v_mul_f32_e32 v20, v20, v246
	v_mul_f32_e32 v21, v21, v247
	v_mul_f32_e32 v22, v22, v248
	v_mul_f32_e32 v23, v23, v249
	v_mul_f32_e32 v24, v24, v246
	v_mul_f32_e32 v25, v25, v247
	v_mul_f32_e32 v26, v26, v248
	v_mul_f32_e32 v27, v27, v249
	v_mul_f32_e32 v28, v28, v246
	v_mul_f32_e32 v29, v29, v247
	v_mul_f32_e32 v30, v30, v248
	v_mul_f32_e32 v31, v31, v249
	v_mov_b32_e32 v235, v233
	s_nop 1
	v_permlane32_swap_b32_e32 v233, v235
	s_nop 1
	v_max_f32_e32 v233, v233, v235
	s_nop 1
	ds_bpermute_b32 v235, v112, v233
	s_waitcnt lgkmcnt(0)
	v_max_f32_e32 v233, v233, v235
	v_max_f32_e32 v233, 0, v233
	v_add_f32_e32 v219, v219, v233
	v_exp_f32_e64 v243, -v233
	v_sub_f32_e32 v118, v118, v233
	v_sub_f32_e32 v119, v119, v233
	v_sub_f32_e32 v120, v120, v233
	v_sub_f32_e32 v121, v121, v233
	v_sub_f32_e32 v126, v126, v233
	v_sub_f32_e32 v127, v127, v233
	v_sub_f32_e32 v128, v128, v233
	v_sub_f32_e32 v129, v129, v233
	v_sub_f32_e32 v134, v134, v233
	v_sub_f32_e32 v135, v135, v233
	v_sub_f32_e32 v136, v136, v233
	v_sub_f32_e32 v137, v137, v233
	v_sub_f32_e32 v142, v142, v233
	v_sub_f32_e32 v143, v143, v233
	v_sub_f32_e32 v144, v144, v233
	v_sub_f32_e32 v145, v145, v233
	v_sub_f32_e32 v228, 0, v219
	v_sub_f32_e32 v229, 0, v219
	v_sub_f32_e32 v230, 0, v219
	v_sub_f32_e32 v231, 0, v219
	v_mul_f32_e32 v221, v221, v243
	ds_write_b32 v216, v243 offset:64
	s_waitcnt lgkmcnt(0)
	ds_read_b128 v[246:249], v217 offset:64
	s_waitcnt lgkmcnt(0)
	v_mul_f32_e32 v32, v32, v246
	v_mul_f32_e32 v33, v33, v247
	v_mul_f32_e32 v34, v34, v248
	v_mul_f32_e32 v35, v35, v249
	v_mul_f32_e32 v36, v36, v246
	v_mul_f32_e32 v37, v37, v247
	v_mul_f32_e32 v38, v38, v248
	v_mul_f32_e32 v39, v39, v249
	v_mul_f32_e32 v40, v40, v246
	v_mul_f32_e32 v41, v41, v247
	v_mul_f32_e32 v42, v42, v248
	v_mul_f32_e32 v43, v43, v249
	v_mul_f32_e32 v44, v44, v246
	v_mul_f32_e32 v45, v45, v247
	v_mul_f32_e32 v46, v46, v248
	v_mul_f32_e32 v47, v47, v249
	v_mul_f32_e32 v48, v48, v246
	v_mul_f32_e32 v49, v49, v247
	v_mul_f32_e32 v50, v50, v248
	v_mul_f32_e32 v51, v51, v249
	v_mul_f32_e32 v52, v52, v246
	v_mul_f32_e32 v53, v53, v247
	v_mul_f32_e32 v54, v54, v248
	v_mul_f32_e32 v55, v55, v249
	v_mul_f32_e32 v56, v56, v246
	v_mul_f32_e32 v57, v57, v247
	v_mul_f32_e32 v58, v58, v248
	v_mul_f32_e32 v59, v59, v249
	v_mul_f32_e32 v60, v60, v246
	v_mul_f32_e32 v61, v61, v247
	v_mul_f32_e32 v62, v62, v248
	v_mul_f32_e32 v63, v63, v249
	s_nop 1
	s_branch .Lat_cont_1
